# prompt attention loop specialised per wave group (no run-time group tests); otherwise as v19 stagger with deferred PV
# speedup vs baseline: 1.0001x; 1.0001x over previous
; template <int VAR>
; __device__ __forceinline__ void attn_unit(const AUnit& u, LAS char* lds) {
;     int tid_ = threadIdx.x; asm volatile("" : "+v"(tid_));
;     const int tid = tid_, wid = __builtin_amdgcn_readfirstlane(tid >> 6), lane = tid & 63, r32 = lane & 31, hi = lane >> 5;
;     const bool wact = wid < u.nwav;
;     const int jmax = u.jbase + (wid >> 1);
;     const bf16_t* gk0; const bf16_t* gk1; const bf16_t* gkr; const bf16_t* gv0; const bf16_t* gv1;
;     {
;         const int rk0 = (2 * wid) * 4 + (lane >> 4), rk1 = rk0 + 4, ph = lane & 15;
;         gk0 = u.Kn + (size_t)rk0 * 128 + ((ph ^ (rk0 & 15)) * 8);
;         gk1 = u.Kn + (size_t)rk1 * 128 + ((ph ^ (rk1 & 15)) * 8);
;         const int rr0 = wid * 8 + (lane >> 3), pr = lane & 7;
;         gkr = u.Kr + (size_t)rr0 * ROPE + ((pr ^ ((rr0 >> 1) & 7)) * 8);
; #pragma unroll
;         for (int i = 0; i < 2; ++i) {
;             const int st = (2 * wid + i) * 2 + (lane >> 5), o16 = lane & 31, kk = (st >> 2) * 8 + (o16 >> 2), c = (st & 3) * 32 + (o16 & 3) * 8;
;             const int key = (kk & ~0xC) | ((kk & 4) << 1) | ((kk & 8) >> 1);
;             const bf16_t* p = u.V + (size_t)key * 128 + c;
;             if (i == 0) gv0 = p; else gv1 = p;
;         }
;     }
;     ...
;     ADMA(0, 0);
;     bf16x8 qr[12];
;     {
;         const int wq = wact ? wid : 0;
;         const bf16_t* qp = u.Q + (size_t)(wq * 32 + r32) * QW + hi * 8;
; #pragma unroll
;         for (int d0 = 0; d0 < 12; ++d0) qr[d0] = *(const bf16x8*)(qp + d0 * 16);
;         float ssn = 0.f, ssr = 0.f;
; #pragma unroll
;         for (int d0 = 0; d0 < 12; ++d0) { float f[8]; unpack8(__builtin_bit_cast(u32x4, qr[d0]), f); float a = 0.f;
; #pragma unroll
;             for (int e = 0; e < 8; ++e) a += f[e] * f[e];
;             if (d0 < 8) ssn += a; else ssr += a; }
;         { auto rr = __builtin_amdgcn_permlane32_swap(__float_as_uint(ssn), __float_as_uint(ssn), false, false); ssn = __uint_as_float(rr[0]) + __uint_as_float(rr[1]); }
;         { auto rr = __builtin_amdgcn_permlane32_swap(__float_as_uint(ssr), __float_as_uint(ssr), false, false); ssr = __uint_as_float(rr[0]) + __uint_as_float(rr[1]); }
;         const float rn = rsqrtf(ssn * (1.f / 128) + NORM_EPS) * QSCALE, rr_ = rsqrtf(ssr * (1.f / ROPE) + NORM_EPS);
.LBB0_941:
	s_lshl_b64 s[2:3], s[10:11], 8
	s_add_u32 s54, s2, s40
	s_addc_u32 s55, s3, s41
	s_mul_i32 s2, s55, 0x1800
	s_mul_hi_u32 s3, s54, 0x1800
	s_add_i32 s3, s3, s2
	s_mul_i32 s2, s54, 0x1800
	v_mov_b32_e32 v181, v0
	s_add_u32 s2, s76, s2
	s_addc_u32 s3, s77, s3
	v_readfirstlane_b32 s5, v181
	s_ashr_i32 s19, s5, 6
	s_lshl_b32 s56, s19, 3
	s_waitcnt lgkmcnt(0)
	v_bfe_u32 v2, v181, 4, 2
	s_waitcnt vmcnt(0)
	v_or_b32_e32 v4, s56, v2
	v_and_b32_e32 v2, 15, v181
	v_ashrrev_i32_e32 v5, 31, v4
	v_bitop3_b32 v10, v4, v2, 11 bitop3:0x6c
	v_bfe_u32 v2, v181, 3, 3
	v_or_b32_e32 v32, 4, v4
	v_lshlrev_b64 v[36:37], 8, v[4:5]
	v_bitop3_b32 v12, v4, v181, 4 bitop3:0x36
	v_or_b32_e32 v4, s56, v2
	v_ashrrev_i32_e32 v33, 31, v32
	v_ashrrev_i32_e32 v5, 31, v4
	v_bfe_u32 v2, v181, 2, 3
	v_lshlrev_b64 v[34:35], 8, v[32:33]
	v_lshlrev_b64 v[38:39], 7, v[4:5]
	v_lshrrev_b32_e32 v33, 1, v4
	v_bitop3_b32 v2, s56, -13, v2 bitop3:0xc8
	v_lshrrev_b32_e32 v4, 1, v181
	s_lshl_b32 s56, s19, 2
	v_and_b32_e32 v4, 8, v4
	s_and_b32 s56, s56, 4
	v_or3_b32 v4, v2, v4, s56
	s_lshl_b32 s56, s19, 11
	s_add_i32 s84, s56, 0
	s_lshl_b32 s56, s19, 10
	s_lshl_b32 s4, s10, 2
	s_add_i32 s87, s56, 0
	s_add_i32 s57, s4, 4
	s_ashr_i32 s91, s5, 7
	v_xor_b32_e32 v14, v33, v181
	s_add_i32 s85, s84, 0x8000
	s_add_i32 s86, s84, 0x8400
	s_add_i32 s88, s87, 0xc000
	s_add_i32 s89, s84, 0x400
	s_lshl_b32 s56, s19, 5
	v_lshl_add_u64 v[8:9], s[42:43], 0, v[36:37]
	v_lshlrev_b32_e32 v42, 4, v10
	v_mov_b32_e32 v43, v3
	v_lshlrev_b32_e32 v12, 4, v12
	v_and_b32_e32 v90, 32, v181
	v_lshlrev_b32_e32 v89, 3, v181
	v_ashrrev_i32_e32 v5, 31, v4
	s_cmp_lt_i32 s19, 8
	v_lshl_add_u64 v[8:9], v[8:9], 0, v[42:43]
	v_lshl_add_u64 v[10:11], s[42:43], 0, v[34:35]
	v_and_b32_e32 v12, 0xf0, v12
	v_mov_b32_e32 v13, v3
	v_lshlrev_b32_e32 v14, 4, v14
	s_mov_b32 m0, s85
	v_and_or_b32 v6, v89, 24, v90
	v_lshlrev_b64 v[40:41], 8, v[4:5]
	s_cselect_b64 s[58:59], -1, 0
	v_lshl_add_u64 v[10:11], v[10:11], 0, v[12:13]
	v_lshl_add_u64 v[12:13], s[48:49], 0, v[38:39]
	v_and_b32_e32 v14, 0x70, v14
	v_mov_b32_e32 v15, v3
	global_load_lds_dwordx4 v[8:9], off
	s_mov_b32 m0, s86
	v_lshl_add_u64 v[4:5], s[46:47], 0, v[40:41]
	v_lshlrev_b32_e32 v2, 1, v6
	v_lshl_add_u64 v[12:13], v[12:13], 0, v[14:15]
	global_load_lds_dwordx4 v[10:11], off
	s_mov_b32 m0, s88
	s_and_b64 s[60:61], s[58:59], exec
	v_and_b32_e32 v180, 31, v181
	v_lshl_add_u64 v[4:5], v[4:5], 0, v[2:3]
	global_load_lds_dwordx4 v[12:13], off
	s_mov_b32 m0, s84
	s_cselect_b32 s60, s56, 0
	v_lshl_add_u64 v[6:7], v[4:5], 0, s[28:29]
	v_bfe_u32 v182, v181, 5, 1
	global_load_lds_dwordx4 v[4:5], off
	v_or_b32_e32 v43, s60, v180
	v_mov_b64_e32 v[4:5], s[2:3]
	s_mov_b32 m0, s89
	v_mad_i64_i32 v[4:5], s[2:3], v43, s45, v[4:5]
	v_lshlrev_b32_e32 v162, 4, v182
	v_mov_b32_e32 v163, v3
	global_load_lds_dwordx4 v[6:7], off
	v_lshl_add_u64 v[8:9], v[4:5], 0, v[162:163]
	global_load_dwordx4 v[28:31], v[8:9], off
	global_load_dwordx4 v[24:27], v[8:9], off offset:32
	global_load_dwordx4 v[20:23], v[8:9], off offset:64
	global_load_dwordx4 v[44:47], v[8:9], off offset:96
	global_load_dwordx4 v[48:51], v[8:9], off offset:128
	global_load_dwordx4 v[52:55], v[8:9], off offset:160
	global_load_dwordx4 v[108:111], v[8:9], off offset:192
	global_load_dwordx4 v[112:115], v[8:9], off offset:224
	global_load_dwordx4 v[12:15], v[8:9], off offset:256
	global_load_dwordx4 v[4:7], v[8:9], off offset:288
	global_load_dwordx4 v[16:19], v[8:9], off offset:320
	s_nop 0
	global_load_dwordx4 v[8:11], v[8:9], off offset:352
	s_lshl_b32 s2, s10, 13
	v_lshl_add_u32 v43, v43, 5, s2
	v_and_b32_e32 v88, 63, v181
	v_lshl_add_u32 v183, v180, 8, 0
	s_add_i32 s10, 0, 0x12000
	s_and_b32 s2, s5, 0x3fffffc0
	s_lshl_b32 s2, s2, 2
	s_add_i32 s90, s2, 0
	v_or_b32_e32 v36, v36, v42
	v_or_b32_e32 v40, v40, v2
	s_add_i32 s90, s90, 0x14000
	v_lshl_add_u64 v[172:173], s[50:51], 0, v[36:37]
	v_lshl_add_u64 v[178:179], s[50:51], 0, v[40:41]
	v_mov_b32_e32 v2, v3
	s_mov_b32 s19, 0
	s_add_i32 s91, s91, s4
	v_bitop3_b32 v212, v162, v89, s21 bitop3:0x78
	v_cmp_gt_u32_e64 s[2:3], 32, v88
	v_lshl_add_u32 v206, v180, 2, s90
	v_mov_b32_e32 v225, 0
	v_mov_b32_e32 v226, 0xf149f2ca
	s_waitcnt vmcnt(0)
	v_and_b32_e32 v104, 0xffff0000, v28
	v_and_b32_e32 v96, 0xffff0000, v24
	v_lshlrev_b32_e32 v106, 16, v28
	v_mul_f32_e32 v28, v104, v104
	v_lshlrev_b32_e32 v100, 16, v24
	v_mul_f32_e32 v24, v96, v96
	v_and_b32_e32 v79, 0xffff0000, v44
	v_and_b32_e32 v78, 0xffff0000, v20
	v_lshlrev_b32_e32 v101, 16, v29
	v_fmac_f32_e32 v28, v106, v106
	v_lshlrev_b32_e32 v94, 16, v25
	v_fmac_f32_e32 v24, v100, v100
	v_lshlrev_b32_e32 v83, 16, v44
	v_lshlrev_b32_e32 v82, 16, v20
	v_lshlrev_b32_e32 v76, 16, v21
	v_and_b32_e32 v74, 0xffff0000, v21
	v_pk_mul_f32 v[20:21], v[78:79], v[78:79]
	v_and_b32_e32 v97, 0xffff0000, v29
	v_fmac_f32_e32 v28, v101, v101
	v_and_b32_e32 v92, 0xffff0000, v25
	v_fmac_f32_e32 v24, v94, v94
	v_lshlrev_b32_e32 v77, 16, v45
	v_pk_fma_f32 v[20:21], v[82:83], v[82:83], v[20:21]
	v_lshlrev_b32_e32 v107, 16, v30
	v_fmac_f32_e32 v28, v97, v97
	v_lshlrev_b32_e32 v102, 16, v26
	v_fmac_f32_e32 v24, v92, v92
	v_and_b32_e32 v75, 0xffff0000, v45
	v_pk_fma_f32 v[20:21], v[76:77], v[76:77], v[20:21]
	v_and_b32_e32 v105, 0xffff0000, v30
	v_fmac_f32_e32 v28, v107, v107
	v_and_b32_e32 v98, 0xffff0000, v26
	v_fmac_f32_e32 v24, v102, v102
	v_lshlrev_b32_e32 v87, 16, v46
	v_lshlrev_b32_e32 v86, 16, v22
	v_pk_fma_f32 v[20:21], v[74:75], v[74:75], v[20:21]
	v_lshlrev_b32_e32 v103, 16, v31
	v_fmac_f32_e32 v28, v105, v105
	v_lshlrev_b32_e32 v95, 16, v27
	v_fmac_f32_e32 v24, v98, v98
	v_and_b32_e32 v85, 0xffff0000, v46
	v_and_b32_e32 v84, 0xffff0000, v22
; __device__ __forceinline__ u32x4 pack8(const float* f) { u32x4 w; w.x = cvtpk(f[0], f[1]); w.y = cvtpk(f[2], f[3]); w.z = cvtpk(f[4], f[5]); w.w = cvtpk(f[6], f[7]); return w; }
; __device__ __forceinline__ bf16x8 pack8(const f32x4& a, const f32x4& b) { u32x4 w; w.x = cpk(a.x, a.y); w.y = cpk(a.z, a.w); w.z = cpk(b.x, b.y); w.w = cpk(b.z, b.w); return __builtin_bit_cast(bf16x8, w); }
; template <int VAR>
; __device__ __forceinline__ void attn_unit(const AUnit& u, LAS char* lds) {
;     ...
;         float ssn = 0.f, ssr = 0.f;
; #pragma unroll
;         for (int d0 = 0; d0 < 12; ++d0) { float f[8]; unpack8(__builtin_bit_cast(u32x4, qr[d0]), f); float a = 0.f;
; #pragma unroll
;             for (int e = 0; e < 8; ++e) a += f[e] * f[e];
;             if (d0 < 8) ssn += a; else ssr += a; }
;         { auto rr = __builtin_amdgcn_permlane32_swap(__float_as_uint(ssn), __float_as_uint(ssn), false, false); ssn = __uint_as_float(rr[0]) + __uint_as_float(rr[1]); }
;         { auto rr = __builtin_amdgcn_permlane32_swap(__float_as_uint(ssr), __float_as_uint(ssr), false, false); ssr = __uint_as_float(rr[0]) + __uint_as_float(rr[1]); }
;         const float rn = rsqrtf(ssn * (1.f / 128) + NORM_EPS) * QSCALE, rr_ = rsqrtf(ssr * (1.f / ROPE) + NORM_EPS);
; #pragma unroll
;         for (int d0 = 0; d0 < 8; ++d0) { float f[8]; unpack8(__builtin_bit_cast(u32x4, qr[d0]), f);
;             const f32x4 g0 = *(const f32x4*)(u.gqn + d0 * 16 + hi * 8), g1 = *(const f32x4*)(u.gqn + d0 * 16 + hi * 8 + 4);
; #pragma unroll
;             for (int e = 0; e < 4; ++e) { f[e] *= rn * g0[e]; f[4 + e] *= rn * g1[e]; }
;             qr[d0] = __builtin_bit_cast(bf16x8, pack8(f)); }
	v_pk_fma_f32 v[20:21], v[86:87], v[86:87], v[20:21]
	v_and_b32_e32 v99, 0xffff0000, v31
	v_fmac_f32_e32 v28, v103, v103
	v_and_b32_e32 v93, 0xffff0000, v27
	v_fmac_f32_e32 v24, v95, v95
	v_lshlrev_b32_e32 v81, 16, v47
	v_lshlrev_b32_e32 v80, 16, v23
	v_pk_fma_f32 v[20:21], v[84:85], v[84:85], v[20:21]
	v_fmac_f32_e32 v28, v99, v99
	v_fmac_f32_e32 v24, v93, v93
	v_and_b32_e32 v73, 0xffff0000, v47
	v_and_b32_e32 v72, 0xffff0000, v23
	v_pk_fma_f32 v[20:21], v[80:81], v[80:81], v[20:21]
	v_add_f32_e32 v24, v28, v24
	v_pk_fma_f32 v[20:21], v[72:73], v[72:73], v[20:21]
	v_and_b32_e32 v65, 0xffff0000, v52
	v_add_f32_e32 v20, v24, v20
	v_and_b32_e32 v64, 0xffff0000, v48
	v_add_f32_e32 v22, v20, v21
	v_lshlrev_b32_e32 v69, 16, v52
	v_lshlrev_b32_e32 v68, 16, v48
	v_pk_mul_f32 v[20:21], v[64:65], v[64:65]
	v_lshlrev_b32_e32 v61, 16, v53
	v_lshlrev_b32_e32 v60, 16, v49
	v_pk_fma_f32 v[20:21], v[68:69], v[68:69], v[20:21]
	v_and_b32_e32 v59, 0xffff0000, v53
	v_and_b32_e32 v58, 0xffff0000, v49
	v_pk_fma_f32 v[20:21], v[60:61], v[60:61], v[20:21]
	v_lshlrev_b32_e32 v71, 16, v54
	v_lshlrev_b32_e32 v70, 16, v50
	v_pk_fma_f32 v[20:21], v[58:59], v[58:59], v[20:21]
	v_and_b32_e32 v67, 0xffff0000, v54
	v_and_b32_e32 v66, 0xffff0000, v50
	v_pk_fma_f32 v[20:21], v[70:71], v[70:71], v[20:21]
	v_lshlrev_b32_e32 v63, 16, v55
	v_lshlrev_b32_e32 v62, 16, v51
	v_pk_fma_f32 v[20:21], v[66:67], v[66:67], v[20:21]
	v_and_b32_e32 v57, 0xffff0000, v55
	v_and_b32_e32 v56, 0xffff0000, v51
	v_pk_fma_f32 v[20:21], v[62:63], v[62:63], v[20:21]
	v_and_b32_e32 v45, 0xffff0000, v112
	v_pk_fma_f32 v[20:21], v[56:57], v[56:57], v[20:21]
	v_and_b32_e32 v44, 0xffff0000, v108
	v_add_f32_e32 v20, v22, v20
	v_add_f32_e32 v22, v20, v21
	v_lshlrev_b32_e32 v49, 16, v112
	v_lshlrev_b32_e32 v48, 16, v108
	v_pk_mul_f32 v[20:21], v[44:45], v[44:45]
	v_lshlrev_b32_e32 v31, 16, v113
	v_lshlrev_b32_e32 v30, 16, v109
	v_pk_fma_f32 v[20:21], v[48:49], v[48:49], v[20:21]
	v_and_b32_e32 v29, 0xffff0000, v113
	v_and_b32_e32 v28, 0xffff0000, v109
	v_pk_fma_f32 v[20:21], v[30:31], v[30:31], v[20:21]
	v_lshlrev_b32_e32 v55, 16, v114
	v_lshlrev_b32_e32 v54, 16, v110
	v_pk_fma_f32 v[20:21], v[28:29], v[28:29], v[20:21]
	v_and_b32_e32 v53, 0xffff0000, v114
	v_and_b32_e32 v52, 0xffff0000, v110
	v_pk_fma_f32 v[20:21], v[54:55], v[54:55], v[20:21]
	v_lshlrev_b32_e32 v51, 16, v115
	v_lshlrev_b32_e32 v50, 16, v111
	v_pk_fma_f32 v[20:21], v[52:53], v[52:53], v[20:21]
	v_and_b32_e32 v47, 0xffff0000, v115
	v_and_b32_e32 v46, 0xffff0000, v111
	v_pk_fma_f32 v[20:21], v[50:51], v[50:51], v[20:21]
	s_nop 0
	v_pk_fma_f32 v[20:21], v[46:47], v[46:47], v[20:21]
	s_nop 0
	v_add_f32_e32 v20, v22, v20
	v_add_f32_e32 v20, v20, v21
	v_mov_b32_e32 v21, v20
	s_nop 1
	v_permlane32_swap_b32_e32 v20, v21
	v_add_f32_e32 v20, v20, v21
	v_fmamk_f32 v20, v20, 0x3c000000, v1
	v_cmp_gt_f32_e32 vcc, s33, v20
	v_mul_f32_e32 v21, 0x4b800000, v20
	s_nop 0
	v_cndmask_b32_e32 v20, v20, v21, vcc
	v_rsq_f32_e32 v20, v20
	s_nop 0
	v_mul_f32_e32 v21, 0x45800000, v20
	v_cndmask_b32_e32 v20, v20, v21, vcc
	v_mul_f32_e32 v91, 0x3dd53b94, v20
	global_load_dwordx4 v[20:23], v90, s[8:9] offset:16
	global_load_dwordx4 v[24:27], v90, s[8:9]
	s_waitcnt vmcnt(0)
	v_mul_f32_e32 v20, v20, v91
	v_mul_f32_e32 v24, v24, v91
	v_mul_f32_e32 v25, v25, v91
	v_mul_f32_e32 v21, v21, v91
	v_mul_f32_e32 v26, v26, v91
	v_mul_f32_e32 v22, v22, v91
	v_mul_f32_e32 v27, v27, v91
	v_mul_f32_e32 v23, v23, v91
	v_mul_f32_e32 v24, v24, v106
	v_mul_f32_e32 v20, v20, v107
	v_mul_f32_e32 v25, v25, v104
	v_mul_f32_e32 v21, v21, v105
	v_mul_f32_e32 v26, v26, v101
	v_mul_f32_e32 v22, v22, v103
	v_mul_f32_e32 v27, v27, v97
	v_mul_f32_e32 v23, v23, v99
	v_cvt_pk_bf16_f32 v114, v24, v25
	v_cvt_pk_bf16_f32 v115, v26, v27
	v_cvt_pk_bf16_f32 v116, v20, v21
	v_cvt_pk_bf16_f32 v117, v22, v23
	global_load_dwordx4 v[20:23], v90, s[8:9] offset:80
	global_load_dwordx4 v[24:27], v90, s[8:9] offset:64
	v_and_b32_e32 v101, 0xffff0000, v8
	v_mov_b32_e32 v103, v101
	v_lshlrev_b32_e32 v97, 16, v9
	v_and_b32_e32 v99, 0xffff0000, v9
	s_waitcnt vmcnt(0)
	v_mul_f32_e32 v20, v20, v91
	v_mul_f32_e32 v24, v24, v91
	v_mul_f32_e32 v25, v25, v91
	v_mul_f32_e32 v21, v21, v91
	v_mul_f32_e32 v26, v26, v91
	v_mul_f32_e32 v22, v22, v91
	v_mul_f32_e32 v27, v27, v91
	v_mul_f32_e32 v23, v23, v91
	v_mul_f32_e32 v24, v24, v100
	v_mul_f32_e32 v20, v20, v102
	v_mul_f32_e32 v25, v25, v96
	v_mul_f32_e32 v21, v21, v98
	v_mul_f32_e32 v26, v26, v94
	v_mul_f32_e32 v22, v22, v95
	v_mul_f32_e32 v27, v27, v92
	v_mul_f32_e32 v23, v23, v93
	v_cvt_pk_bf16_f32 v118, v24, v25
	v_cvt_pk_bf16_f32 v119, v26, v27
	v_cvt_pk_bf16_f32 v120, v20, v21
	v_cvt_pk_bf16_f32 v121, v22, v23
	global_load_dwordx4 v[20:23], v90, s[8:9] offset:144
	global_load_dwordx4 v[24:27], v90, s[8:9] offset:128
	v_and_b32_e32 v100, 0xffff0000, v4
	v_lshlrev_b32_e32 v96, 16, v5
	v_and_b32_e32 v98, 0xffff0000, v5
	v_lshlrev_b32_e32 v92, 16, v6
	v_and_b32_e32 v94, 0xffff0000, v6
	v_mov_b32_e32 v9, v92
	v_lshlrev_b32_e32 v93, 16, v10
	v_and_b32_e32 v95, 0xffff0000, v10
	s_waitcnt vmcnt(0)
	v_mul_f32_e32 v20, v91, v20
	v_mul_f32_e32 v24, v91, v24
	v_mul_f32_e32 v25, v91, v25
	v_mul_f32_e32 v21, v91, v21
	v_mul_f32_e32 v26, v91, v26
	v_mul_f32_e32 v22, v91, v22
	v_mul_f32_e32 v27, v91, v27
	v_mul_f32_e32 v23, v91, v23
	v_mul_f32_e32 v24, v24, v82
	v_mul_f32_e32 v20, v20, v86
	v_mul_f32_e32 v25, v25, v78
	v_mul_f32_e32 v21, v21, v84
	v_mul_f32_e32 v26, v26, v76
	v_mul_f32_e32 v22, v22, v80
	v_mul_f32_e32 v27, v27, v74
	v_mul_f32_e32 v23, v23, v72
	v_cvt_pk_bf16_f32 v122, v24, v25
	v_cvt_pk_bf16_f32 v123, v26, v27
	v_cvt_pk_bf16_f32 v124, v20, v21
	v_cvt_pk_bf16_f32 v125, v22, v23
	global_load_dwordx4 v[20:23], v90, s[8:9] offset:208
	global_load_dwordx4 v[24:27], v90, s[8:9] offset:192
	v_lshlrev_b32_e32 v80, 16, v12
	v_and_b32_e32 v12, 0xffff0000, v12
	v_and_b32_e32 v78, 0xffff0000, v13
	v_lshlrev_b32_e32 v72, 16, v14
	v_and_b32_e32 v14, 0xffff0000, v14
	v_lshlrev_b32_e32 v84, 16, v7
	v_mov_b32_e32 v10, v14
	v_and_b32_e32 v86, 0xffff0000, v7
	v_mov_b32_e32 v5, v84
	v_mov_b32_e32 v7, v86
	s_waitcnt vmcnt(0)
; __device__ __forceinline__ u32x4 pack8(const float* f) { u32x4 w; w.x = cvtpk(f[0], f[1]); w.y = cvtpk(f[2], f[3]); w.z = cvtpk(f[4], f[5]); w.w = cvtpk(f[6], f[7]); return w; }
; __device__ __forceinline__ bf16x8 pack8(const f32x4& a, const f32x4& b) { u32x4 w; w.x = cpk(a.x, a.y); w.y = cpk(a.z, a.w); w.z = cpk(b.x, b.y); w.w = cpk(b.z, b.w); return __builtin_bit_cast(bf16x8, w); }
; template <int VAR>
; __device__ __forceinline__ void attn_unit(const AUnit& u, LAS char* lds) {
;     ...
;         for (int d0 = 0; d0 < 8; ++d0) { float f[8]; unpack8(__builtin_bit_cast(u32x4, qr[d0]), f);
;             const f32x4 g0 = *(const f32x4*)(u.gqn + d0 * 16 + hi * 8), g1 = *(const f32x4*)(u.gqn + d0 * 16 + hi * 8 + 4);
; #pragma unroll
;             for (int e = 0; e < 4; ++e) { f[e] *= rn * g0[e]; f[4 + e] *= rn * g1[e]; }
;             qr[d0] = __builtin_bit_cast(bf16x8, pack8(f)); }
;         const int pos = u.pos0 + wq * 32 + r32;
; #pragma unroll
;         for (int a = 0; a < 2; ++a) { float x1[8], x2[8]; unpack8(__builtin_bit_cast(u32x4, qr[8 + a]), x1); unpack8(__builtin_bit_cast(u32x4, qr[10 + a]), x2);
;             const int i0 = a * 16 + hi * 8;
;             const f32x4 ga0 = *(const f32x4*)(u.gqr + i0), ga1 = *(const f32x4*)(u.gqr + i0 + 4), gb0 = *(const f32x4*)(u.gqr + 32 + i0), gb1 = *(const f32x4*)(u.gqr + 32 + i0 + 4);
;             float y1[8], y2[8];
; #pragma unroll
;             for (int e = 0; e < 8; ++e) { const float v1 = x1[e] * rr_ * (e < 4 ? ga0[e & 3] : ga1[e & 3]), v2 = x2[e] * rr_ * (e < 4 ? gb0[e & 3] : gb1[e & 3]);
;                 const float2 cs = u.tab[pos * 32 + i0 + e];
	v_mul_f32_e32 v20, v91, v20
	v_mul_f32_e32 v24, v91, v24
	v_mul_f32_e32 v25, v91, v25
	v_mul_f32_e32 v21, v91, v21
	v_mul_f32_e32 v26, v91, v26
	v_mul_f32_e32 v22, v91, v22
	v_mul_f32_e32 v27, v91, v27
	v_mul_f32_e32 v23, v91, v23
	v_mul_f32_e32 v24, v24, v83
	v_mul_f32_e32 v20, v20, v87
	v_mul_f32_e32 v25, v25, v79
	v_mul_f32_e32 v21, v21, v85
	v_mul_f32_e32 v26, v26, v77
	v_mul_f32_e32 v22, v22, v81
	v_mul_f32_e32 v27, v27, v75
	v_mul_f32_e32 v23, v23, v73
	v_cvt_pk_bf16_f32 v126, v24, v25
	v_cvt_pk_bf16_f32 v127, v26, v27
	v_cvt_pk_bf16_f32 v128, v20, v21
	v_cvt_pk_bf16_f32 v129, v22, v23
	global_load_dwordx4 v[20:23], v90, s[8:9] offset:272
	global_load_dwordx4 v[24:27], v90, s[8:9] offset:256
	v_lshlrev_b32_e32 v73, 16, v18
	v_lshlrev_b32_e32 v81, 16, v16
	v_and_b32_e32 v79, 0xffff0000, v17
	v_lshlrev_b32_e32 v85, 16, v11
	v_and_b32_e32 v87, 0xffff0000, v11
	v_mov_b32_e32 v11, v94
	s_waitcnt vmcnt(0)
	v_mul_f32_e32 v20, v91, v20
	v_mul_f32_e32 v24, v91, v24
	v_mul_f32_e32 v25, v91, v25
	v_mul_f32_e32 v21, v91, v21
	v_mul_f32_e32 v26, v91, v26
	v_mul_f32_e32 v22, v91, v22
	v_mul_f32_e32 v27, v91, v27
	v_mul_f32_e32 v23, v91, v23
	v_mul_f32_e32 v24, v24, v68
	v_mul_f32_e32 v20, v20, v70
	v_mul_f32_e32 v25, v25, v64
	v_mul_f32_e32 v21, v21, v66
	v_mul_f32_e32 v26, v26, v60
	v_mul_f32_e32 v22, v22, v62
	v_mul_f32_e32 v27, v27, v58
	v_mul_f32_e32 v23, v23, v56
	v_cvt_pk_bf16_f32 v130, v24, v25
	v_cvt_pk_bf16_f32 v131, v26, v27
	v_cvt_pk_bf16_f32 v132, v20, v21
	v_cvt_pk_bf16_f32 v133, v22, v23
	global_load_dwordx4 v[20:23], v90, s[8:9] offset:336
	global_load_dwordx4 v[24:27], v90, s[8:9] offset:320
	v_lshl_or_b32 v64, v182, 3, v43
	v_lshlrev_b32_e32 v66, 16, v15
	v_and_b32_e32 v70, 0xffff0000, v15
	v_and_b32_e32 v15, 0xffff0000, v18
	v_lshlrev_b32_e32 v18, 16, v13
	v_and_b32_e32 v13, 0xffff0000, v16
	v_or_b32_e32 v16, 16, v64
	v_mov_b32_e32 v102, v13
	v_pk_mul_f32 v[102:103], v[102:103], v[102:103]
	v_mov_b32_e32 v6, v70
	s_waitcnt vmcnt(0)
	v_mul_f32_e32 v20, v91, v20
	v_mul_f32_e32 v24, v91, v24
	v_mul_f32_e32 v25, v91, v25
	v_mul_f32_e32 v21, v91, v21
	v_mul_f32_e32 v26, v91, v26
	v_mul_f32_e32 v22, v91, v22
	v_mul_f32_e32 v27, v91, v27
	v_mul_f32_e32 v23, v91, v23
	v_mul_f32_e32 v24, v24, v69
	v_mul_f32_e32 v20, v20, v71
	v_mul_f32_e32 v25, v25, v65
	v_mul_f32_e32 v21, v21, v67
	v_mul_f32_e32 v26, v26, v61
	v_mul_f32_e32 v22, v22, v63
	v_mul_f32_e32 v27, v27, v59
	v_mul_f32_e32 v23, v23, v57
	v_cvt_pk_bf16_f32 v134, v24, v25
	v_cvt_pk_bf16_f32 v135, v26, v27
	v_cvt_pk_bf16_f32 v136, v20, v21
	v_cvt_pk_bf16_f32 v137, v22, v23
	global_load_dwordx4 v[20:23], v90, s[8:9] offset:400
	global_load_dwordx4 v[24:27], v90, s[8:9] offset:384
	v_ashrrev_i32_e32 v65, 31, v64
	v_lshl_add_u64 v[60:61], v[64:65], 3, s[6:7]
	v_lshlrev_b32_e32 v67, 16, v19
	v_and_b32_e32 v71, 0xffff0000, v19
	v_lshlrev_b32_e32 v19, 16, v17
	v_ashrrev_i32_e32 v17, 31, v16
	v_lshl_add_u64 v[64:65], v[16:17], 3, s[6:7]
	v_mov_b32_e32 v16, v18
	v_mov_b32_e32 v17, v96
	s_waitcnt vmcnt(0)
	v_mul_f32_e32 v20, v91, v20
	v_mul_f32_e32 v24, v91, v24
	v_mul_f32_e32 v25, v91, v25
	v_mul_f32_e32 v21, v91, v21
	v_mul_f32_e32 v26, v91, v26
	v_mul_f32_e32 v22, v91, v22
	v_mul_f32_e32 v27, v91, v27
	v_mul_f32_e32 v23, v91, v23
	v_mul_f32_e32 v24, v24, v48
	v_mul_f32_e32 v20, v20, v54
	v_mul_f32_e32 v25, v25, v44
	v_mul_f32_e32 v21, v21, v52
	v_mul_f32_e32 v26, v26, v30
	v_mul_f32_e32 v22, v22, v50
	v_mul_f32_e32 v27, v27, v28
	v_mul_f32_e32 v23, v23, v46
	v_cvt_pk_bf16_f32 v138, v24, v25
	v_cvt_pk_bf16_f32 v139, v26, v27
	v_cvt_pk_bf16_f32 v140, v20, v21
	v_cvt_pk_bf16_f32 v141, v22, v23
	global_load_dwordx4 v[20:23], v90, s[8:9] offset:464
	global_load_dwordx4 v[24:27], v90, s[8:9] offset:448
	s_waitcnt vmcnt(0)
	v_mul_f32_e32 v20, v91, v20
	v_mul_f32_e32 v24, v91, v24
	v_mul_f32_e32 v25, v91, v25
	v_mul_f32_e32 v21, v91, v21
	v_mul_f32_e32 v26, v91, v26
	v_mul_f32_e32 v22, v91, v22
	v_mul_f32_e32 v27, v91, v27
	v_mul_f32_e32 v23, v91, v23
	v_mul_f32_e32 v24, v24, v49
	v_mul_f32_e32 v20, v20, v55
	v_mul_f32_e32 v25, v25, v45
	v_mul_f32_e32 v21, v21, v53
	v_mul_f32_e32 v26, v26, v31
	v_mul_f32_e32 v22, v22, v51
	v_mul_f32_e32 v27, v27, v29
	v_mul_f32_e32 v23, v23, v47
	v_cvt_pk_bf16_f32 v142, v24, v25
	v_cvt_pk_bf16_f32 v143, v26, v27
	v_cvt_pk_bf16_f32 v144, v20, v21
	v_cvt_pk_bf16_f32 v145, v22, v23
	global_load_dwordx4 v[20:23], v90, s[36:37]
	global_load_dwordx4 v[24:27], v90, s[36:37] offset:16
	global_load_dwordx4 v[28:31], v90, s[36:37] offset:128
	global_load_dwordx4 v[44:47], v90, s[36:37] offset:144
	global_load_dwordx4 v[48:51], v[60:61], off offset:48
	global_load_dwordx4 v[52:55], v[60:61], off offset:32
	global_load_dwordx4 v[56:59], v[60:61], off offset:16
	s_nop 0
	global_load_dwordx4 v[60:63], v[60:61], off
	s_waitcnt vmcnt(0)
; __device__ __forceinline__ u32x4 pack8(const float* f) { u32x4 w; w.x = cvtpk(f[0], f[1]); w.y = cvtpk(f[2], f[3]); w.z = cvtpk(f[4], f[5]); w.w = cvtpk(f[6], f[7]); return w; }
; __device__ __forceinline__ bf16x8 pack8(const f32x4& a, const f32x4& b) { u32x4 w; w.x = cpk(a.x, a.y); w.y = cpk(a.z, a.w); w.z = cpk(b.x, b.y); w.w = cpk(b.z, b.w); return __builtin_bit_cast(bf16x8, w); }
; template <int VAR>
; __device__ __forceinline__ void attn_unit(const AUnit& u, LAS char* lds) {
;     ...
;         const int pos = u.pos0 + wq * 32 + r32;
; #pragma unroll
;         for (int a = 0; a < 2; ++a) { float x1[8], x2[8]; unpack8(__builtin_bit_cast(u32x4, qr[8 + a]), x1); unpack8(__builtin_bit_cast(u32x4, qr[10 + a]), x2);
;             const int i0 = a * 16 + hi * 8;
;             const f32x4 ga0 = *(const f32x4*)(u.gqr + i0), ga1 = *(const f32x4*)(u.gqr + i0 + 4), gb0 = *(const f32x4*)(u.gqr + 32 + i0), gb1 = *(const f32x4*)(u.gqr + 32 + i0 + 4);
;             float y1[8], y2[8];
; #pragma unroll
;             for (int e = 0; e < 8; ++e) { const float v1 = x1[e] * rr_ * (e < 4 ? ga0[e & 3] : ga1[e & 3]), v2 = x2[e] * rr_ * (e < 4 ? gb0[e & 3] : gb1[e & 3]);
;                 const float2 cs = u.tab[pos * 32 + i0 + e];
;                 y1[e] = (v1 * cs.x - v2 * cs.y) * QSCALE; y2[e] = (v2 * cs.x + v1 * cs.y) * QSCALE; }
;             qr[8 + a] = __builtin_bit_cast(bf16x8, pack8(y1)); qr[10 + a] = __builtin_bit_cast(bf16x8, pack8(y2)); }
	v_mov_b32_e32 v82, v20
	v_mov_b32_e32 v68, v26
	v_lshlrev_b32_e32 v20, 16, v4
	v_mov_b32_e32 v69, v46
	v_mov_b32_e32 v46, v27
	v_mov_b32_e32 v26, v12
	v_mov_b32_e32 v27, v100
	v_mov_b32_e32 v74, v24
	v_mov_b32_e32 v75, v44
	v_mov_b32_e32 v44, v25
	v_mov_b32_e32 v24, v80
	v_mov_b32_e32 v25, v20
	v_pk_mul_f32 v[26:27], v[26:27], v[26:27]
	v_mov_b32_e32 v83, v28
	v_mov_b32_e32 v28, v21
	v_lshlrev_b32_e32 v21, 16, v8
	v_pk_fma_f32 v[24:25], v[24:25], v[24:25], v[26:27]
	v_mov_b32_e32 v76, v22
	v_mov_b32_e32 v77, v30
	v_mov_b32_e32 v30, v23
	v_mov_b32_e32 v22, v78
	v_mov_b32_e32 v23, v98
	v_pk_fma_f32 v[16:17], v[16:17], v[16:17], v[24:25]
	v_mov_b32_e32 v26, v81
	v_mov_b32_e32 v27, v21
	v_mov_b32_e32 v8, v72
	v_pk_fma_f32 v[16:17], v[22:23], v[22:23], v[16:17]
	v_mov_b32_e32 v22, v19
	v_mov_b32_e32 v23, v97
	v_pk_fma_f32 v[26:27], v[26:27], v[26:27], v[102:103]
	v_pk_fma_f32 v[8:9], v[8:9], v[8:9], v[16:17]
	v_mov_b32_e32 v24, v79
	v_mov_b32_e32 v25, v99
	v_pk_fma_f32 v[22:23], v[22:23], v[22:23], v[26:27]
	v_mov_b32_e32 v4, v66
	v_pk_fma_f32 v[8:9], v[10:11], v[10:11], v[8:9]
	v_mov_b32_e32 v10, v73
	v_mov_b32_e32 v11, v93
	v_pk_fma_f32 v[22:23], v[24:25], v[24:25], v[22:23]
	v_pk_fma_f32 v[4:5], v[4:5], v[4:5], v[8:9]
	v_mov_b32_e32 v16, v15
	v_mov_b32_e32 v17, v95
	v_pk_fma_f32 v[10:11], v[10:11], v[10:11], v[22:23]
	v_pk_fma_f32 v[4:5], v[6:7], v[6:7], v[4:5]
	v_mov_b32_e32 v6, v67
	v_mov_b32_e32 v7, v85
	v_pk_fma_f32 v[10:11], v[16:17], v[16:17], v[10:11]
	v_mov_b32_e32 v8, v71
	v_mov_b32_e32 v9, v87
	v_pk_fma_f32 v[6:7], v[6:7], v[6:7], v[10:11]
	v_pk_add_f32 v[4:5], v[4:5], v[4:5] op_sel:[0,1] op_sel_hi:[1,0]
	v_pk_fma_f32 v[6:7], v[8:9], v[8:9], v[6:7]
	s_nop 0
	v_pk_add_f32 v[4:5], v[4:5], v[6:7]
	s_nop 0
	v_pk_add_f32 v[4:5], v[4:5], v[6:7] op_sel:[0,1] op_sel_hi:[1,0]
	s_nop 0
	v_mov_b32_e32 v5, v4
	s_nop 1
	v_permlane32_swap_b32_e32 v4, v5
	v_add_f32_e32 v4, v4, v5
	v_fmamk_f32 v4, v4, 0x3c800000, v1
	v_cmp_gt_f32_e32 vcc, s33, v4
	v_mul_f32_e32 v5, 0x4b800000, v4
	s_nop 0
	v_cndmask_b32_e32 v4, v4, v5, vcc
	v_rsq_f32_e32 v4, v4
	s_nop 0
	v_mul_f32_e32 v5, 0x45800000, v4
	v_cndmask_b32_e32 v102, v4, v5, vcc
	v_pk_mul_f32 v[4:5], v[102:103], v[80:81] op_sel_hi:[0,1]
	v_pk_mul_f32 v[4:5], v[4:5], v[82:83]
	v_pk_mul_f32 v[20:21], v[102:103], v[20:21] op_sel_hi:[0,1]
	v_pk_mul_f32 v[6:7], v[4:5], v[60:61]
	v_pk_mul_f32 v[4:5], v[4:5], v[60:61] op_sel:[1,0] op_sel_hi:[0,1]
	v_add_f32_e32 v4, v4, v5
	v_mul_f32_e32 v9, 0x3dd53b94, v4
	v_pk_mul_f32 v[4:5], v[102:103], v[12:13] op_sel_hi:[0,1]
	v_sub_f32_e32 v6, v6, v7
	v_pk_mul_f32 v[4:5], v[4:5], v[28:29]
	v_mul_f32_e32 v8, 0x3dd53b94, v6
	v_pk_mul_f32 v[6:7], v[4:5], v[62:63]
	v_pk_mul_f32 v[4:5], v[4:5], v[62:63] op_sel:[1,0] op_sel_hi:[0,1]
	v_add_f32_e32 v4, v4, v5
	v_mul_f32_e32 v11, 0x3dd53b94, v4
	v_pk_mul_f32 v[4:5], v[102:103], v[18:19] op_sel_hi:[0,1]
	v_sub_f32_e32 v6, v6, v7
	v_pk_mul_f32 v[4:5], v[4:5], v[76:77]
	v_mul_f32_e32 v10, 0x3dd53b94, v6
	v_pk_mul_f32 v[6:7], v[4:5], v[56:57]
	v_pk_mul_f32 v[4:5], v[4:5], v[56:57] op_sel:[1,0] op_sel_hi:[0,1]
	v_add_f32_e32 v4, v4, v5
	v_mul_f32_e32 v13, 0x3dd53b94, v4
	v_pk_mul_f32 v[4:5], v[102:103], v[78:79] op_sel_hi:[0,1]
	v_sub_f32_e32 v6, v6, v7
	v_pk_mul_f32 v[4:5], v[4:5], v[30:31]
	v_mul_f32_e32 v12, 0x3dd53b94, v6
	v_pk_mul_f32 v[6:7], v[4:5], v[58:59]
	v_pk_mul_f32 v[4:5], v[4:5], v[58:59] op_sel:[1,0] op_sel_hi:[0,1]
	v_add_f32_e32 v4, v4, v5
	v_mul_f32_e32 v17, 0x3dd53b94, v4
	v_pk_mul_f32 v[4:5], v[102:103], v[72:73] op_sel_hi:[0,1]
	v_sub_f32_e32 v6, v6, v7
	v_pk_mul_f32 v[4:5], v[4:5], v[74:75]
	v_mul_f32_e32 v16, 0x3dd53b94, v6
	v_pk_mul_f32 v[6:7], v[4:5], v[52:53]
	v_pk_mul_f32 v[4:5], v[4:5], v[52:53] op_sel:[1,0] op_sel_hi:[0,1]
	v_add_f32_e32 v4, v4, v5
	v_mul_f32_e32 v19, 0x3dd53b94, v4
	v_pk_mul_f32 v[4:5], v[102:103], v[14:15] op_sel_hi:[0,1]
	v_sub_f32_e32 v6, v6, v7
	v_pk_mul_f32 v[4:5], v[4:5], v[44:45]
	v_mul_f32_e32 v18, 0x3dd53b94, v6
	v_pk_mul_f32 v[6:7], v[4:5], v[54:55]
	v_pk_mul_f32 v[4:5], v[4:5], v[54:55] op_sel:[1,0] op_sel_hi:[0,1]
	v_add_f32_e32 v4, v4, v5
	v_mul_f32_e32 v15, 0x3dd53b94, v4
	v_pk_mul_f32 v[4:5], v[102:103], v[66:67] op_sel_hi:[0,1]
	v_sub_f32_e32 v6, v6, v7
	v_pk_mul_f32 v[4:5], v[4:5], v[68:69]
	v_mul_f32_e32 v14, 0x3dd53b94, v6
	v_pk_mul_f32 v[6:7], v[4:5], v[48:49]
	v_pk_mul_f32 v[4:5], v[4:5], v[48:49] op_sel:[1,0] op_sel_hi:[0,1]
	v_add_f32_e32 v4, v4, v5
	v_mul_f32_e32 v23, 0x3dd53b94, v4
	v_pk_mul_f32 v[4:5], v[102:103], v[70:71] op_sel_hi:[0,1]
	v_sub_f32_e32 v6, v6, v7
	v_pk_mul_f32 v[4:5], v[4:5], v[46:47]
	v_mul_f32_e32 v22, 0x3dd53b94, v6
	v_pk_mul_f32 v[6:7], v[4:5], v[50:51]
	v_pk_mul_f32 v[4:5], v[4:5], v[50:51] op_sel:[1,0] op_sel_hi:[0,1]
	v_sub_f32_e32 v6, v6, v7
	v_add_f32_e32 v4, v4, v5
	v_mul_f32_e32 v6, 0x3dd53b94, v6
	v_mul_f32_e32 v4, 0x3dd53b94, v4
	v_cvt_pk_bf16_f32 v146, v8, v10
	v_cvt_pk_bf16_f32 v147, v12, v16
	v_cvt_pk_bf16_f32 v148, v18, v14
	v_cvt_pk_bf16_f32 v149, v22, v6
	v_cvt_pk_bf16_f32 v150, v9, v11
	v_cvt_pk_bf16_f32 v151, v13, v17
	v_cvt_pk_bf16_f32 v152, v19, v15
	v_cvt_pk_bf16_f32 v153, v23, v4
	global_load_dwordx4 v[4:7], v90, s[36:37] offset:80
	global_load_dwordx4 v[8:11], v90, s[36:37] offset:64
	global_load_dwordx4 v[12:15], v90, s[36:37] offset:208
	global_load_dwordx4 v[16:19], v90, s[36:37] offset:192
	s_waitcnt vmcnt(0)
	v_mov_b32_e32 v22, v8
	v_mov_b32_e32 v23, v16
	v_pk_mul_f32 v[48:49], v[20:21], v[22:23]
	global_load_dwordx4 v[20:23], v[64:65], off offset:48
	global_load_dwordx4 v[24:27], v[64:65], off offset:32
	global_load_dwordx4 v[28:31], v[64:65], off offset:16
	global_load_dwordx4 v[44:47], v[64:65], off
	v_mov_b32_e32 v16, v9
	s_waitcnt vmcnt(0)
; #define LAS __attribute__((address_space(3)))
; __device__ __forceinline__ u32x4 pack8(const float* f) { u32x4 w; w.x = cvtpk(f[0], f[1]); w.y = cvtpk(f[2], f[3]); w.z = cvtpk(f[4], f[5]); w.w = cvtpk(f[6], f[7]); return w; }
; __device__ __forceinline__ int v_rd_base(int lane) { return ((lane & 3) << 3) | (((lane >> 2) & 3) << 6) | (((lane >> 4) & 1) << 5) | (((lane >> 5) & 1) << 8); }
; #define AWAITV() asm volatile("s_waitcnt vmcnt(0)" ::: "memory")
; __device__ __forceinline__ bf16x8 pack8(const f32x4& a, const f32x4& b) { u32x4 w; w.x = cpk(a.x, a.y); w.y = cpk(a.z, a.w); w.z = cpk(b.x, b.y); w.w = cpk(b.z, b.w); return __builtin_bit_cast(bf16x8, w); }
; template <int VAR>
; __device__ __forceinline__ void attn_unit(const AUnit& u, LAS char* lds) {
;     ...
;             for (int e = 0; e < 8; ++e) { const float v1 = x1[e] * rr_ * (e < 4 ? ga0[e & 3] : ga1[e & 3]), v2 = x2[e] * rr_ * (e < 4 ? gb0[e & 3] : gb1[e & 3]);
;                 const float2 cs = u.tab[pos * 32 + i0 + e];
;                 y1[e] = (v1 * cs.x - v2 * cs.y) * QSCALE; y2[e] = (v2 * cs.x + v1 * cs.y) * QSCALE; }
;             qr[8 + a] = __builtin_bit_cast(bf16x8, pack8(y1)); qr[10 + a] = __builtin_bit_cast(bf16x8, pack8(y2)); }
;     }
;     float m_reg = -1e30f, l_reg = 0.f; f32x16 o[4]; o[0] = f32x16{}; o[1] = f32x16{}; o[2] = f32x16{}; o[3] = f32x16{};
;     LAS float* wsf = (LAS float*)(lds + OFF_WS) + wid * 64; LAS float* li_l = wsf; LAS float* al_l = wsf + 32;
;     const int vb0 = (int)(unsigned)(uintptr_t)lds + v_rd_base(lane);
;     AWAITV();
;     __syncthreads();
	v_pk_mul_f32 v[50:51], v[48:49], v[44:45]
	s_nop 0
	v_sub_f32_e32 v8, v50, v51
	v_pk_mul_f32 v[44:45], v[48:49], v[44:45] op_sel:[1,0] op_sel_hi:[0,1]
	v_mul_f32_e32 v43, 0x3dd53b94, v8
	v_add_f32_e32 v8, v44, v45
	v_pk_mul_f32 v[44:45], v[102:103], v[100:101] op_sel_hi:[0,1]
	v_mul_f32_e32 v48, 0x3dd53b94, v8
	v_pk_mul_f32 v[8:9], v[44:45], v[16:17]
	s_nop 0
	v_pk_mul_f32 v[16:17], v[8:9], v[46:47]
	v_pk_mul_f32 v[8:9], v[8:9], v[46:47] op_sel:[1,0] op_sel_hi:[0,1]
	v_sub_f32_e32 v16, v16, v17
	v_add_f32_e32 v8, v8, v9
	v_mul_f32_e32 v44, 0x3dd53b94, v16
	v_mul_f32_e32 v45, 0x3dd53b94, v8
	v_pk_mul_f32 v[8:9], v[102:103], v[96:97] op_sel_hi:[0,1]
	v_mov_b32_e32 v16, v10
	v_mov_b32_e32 v17, v18
	v_pk_mul_f32 v[8:9], v[8:9], v[16:17]
	v_mov_b32_e32 v18, v11
	v_pk_mul_f32 v[16:17], v[8:9], v[28:29]
	v_pk_mul_f32 v[8:9], v[8:9], v[28:29] op_sel:[1,0] op_sel_hi:[0,1]
	v_add_f32_e32 v8, v8, v9
	v_sub_f32_e32 v10, v16, v17
	v_mul_f32_e32 v17, 0x3dd53b94, v8
	v_pk_mul_f32 v[8:9], v[102:103], v[98:99] op_sel_hi:[0,1]
	v_pk_mul_f32 v[8:9], v[8:9], v[18:19]
	v_mul_f32_e32 v16, 0x3dd53b94, v10
	v_pk_mul_f32 v[10:11], v[8:9], v[30:31]
	v_pk_mul_f32 v[8:9], v[8:9], v[30:31] op_sel:[1,0] op_sel_hi:[0,1]
	v_sub_f32_e32 v10, v10, v11
	v_add_f32_e32 v8, v8, v9
	v_mul_f32_e32 v18, 0x3dd53b94, v10
	v_mul_f32_e32 v19, 0x3dd53b94, v8
	v_pk_mul_f32 v[8:9], v[102:103], v[92:93] op_sel_hi:[0,1]
	v_mov_b32_e32 v10, v4
	v_mov_b32_e32 v11, v12
	v_pk_mul_f32 v[8:9], v[8:9], v[10:11]
	v_mov_b32_e32 v12, v5
	v_pk_mul_f32 v[10:11], v[8:9], v[24:25]
	v_pk_mul_f32 v[8:9], v[8:9], v[24:25] op_sel:[1,0] op_sel_hi:[0,1]
	v_sub_f32_e32 v4, v10, v11
	v_mul_f32_e32 v10, 0x3dd53b94, v4
	v_add_f32_e32 v4, v8, v9
	v_pk_mul_f32 v[8:9], v[102:103], v[94:95] op_sel_hi:[0,1]
	v_mul_f32_e32 v11, 0x3dd53b94, v4
	v_pk_mul_f32 v[4:5], v[8:9], v[12:13]
	v_cvt_pk_bf16_f32 v154, v43, v44
	v_cvt_pk_bf16_f32 v155, v16, v18
	v_mov_b32_e32 v16, v3
	v_pk_mul_f32 v[8:9], v[4:5], v[26:27]
	v_pk_mul_f32 v[4:5], v[4:5], v[26:27] op_sel:[1,0] op_sel_hi:[0,1]
	v_sub_f32_e32 v8, v8, v9
	v_add_f32_e32 v4, v4, v5
	v_mul_f32_e32 v12, 0x3dd53b94, v8
	v_mul_f32_e32 v13, 0x3dd53b94, v4
	v_pk_mul_f32 v[4:5], v[102:103], v[84:85] op_sel_hi:[0,1]
	v_mov_b32_e32 v8, v6
	v_mov_b32_e32 v9, v14
	v_pk_mul_f32 v[4:5], v[4:5], v[8:9]
	v_mov_b32_e32 v14, v7
	v_pk_mul_f32 v[8:9], v[4:5], v[20:21]
	v_pk_mul_f32 v[4:5], v[4:5], v[20:21] op_sel:[1,0] op_sel_hi:[0,1]
	v_add_f32_e32 v4, v4, v5
	v_sub_f32_e32 v6, v8, v9
	v_mul_f32_e32 v9, 0x3dd53b94, v4
	v_pk_mul_f32 v[4:5], v[102:103], v[86:87] op_sel_hi:[0,1]
	v_pk_mul_f32 v[4:5], v[4:5], v[14:15]
	v_mul_f32_e32 v8, 0x3dd53b94, v6
	v_pk_mul_f32 v[6:7], v[4:5], v[22:23]
	v_pk_mul_f32 v[4:5], v[4:5], v[22:23] op_sel:[1,0] op_sel_hi:[0,1]
	v_sub_f32_e32 v6, v6, v7
	v_add_f32_e32 v4, v4, v5
	v_mul_f32_e32 v6, 0x3dd53b94, v6
	v_mul_f32_e32 v4, 0x3dd53b94, v4
	v_lshlrev_b32_e32 v5, 4, v181
	v_cvt_pk_bf16_f32 v156, v10, v12
	v_cvt_pk_bf16_f32 v157, v8, v6
	v_cvt_pk_bf16_f32 v158, v48, v45
	v_cvt_pk_bf16_f32 v159, v17, v19
	v_cvt_pk_bf16_f32 v160, v11, v13
	v_cvt_pk_bf16_f32 v161, v9, v4
	v_lshlrev_b32_e32 v4, 3, v88
	v_and_b32_e32 v6, 0xc0, v5
	v_lshlrev_b32_e32 v7, 1, v181
	v_and_or_b32 v6, v4, 24, v6
	v_and_b32_e32 v7, 32, v7
	v_and_b32_e32 v4, 0x100, v4
	v_or3_b32 v4, v6, v7, v4
	v_add_u32_e32 v163, 0, v4
	v_and_b32_e32 v4, 0xf0, v5
	v_bitop3_b32 v185, v162, v4, 32 bitop3:0x36
	v_bitop3_b32 v186, v162, v4, 64 bitop3:0x36
	v_bitop3_b32 v187, v162, v4, s24 bitop3:0x36
	v_bitop3_b32 v207, v162, v4, s23 bitop3:0x36
	v_bitop3_b32 v208, v162, v4, s25 bitop3:0x36
	v_bitop3_b32 v209, v162, v4, s14 bitop3:0x36
	v_bitop3_b32 v210, v162, v4, s15 bitop3:0x36
	v_lshlrev_b32_e32 v4, 7, v180
	v_sub_u32_e32 v211, v183, v4
	v_add_u32_e32 v224, s10, v4
	v_bitop3_b32 v4, v32, 15, v181 bitop3:0x48
	v_lshl_or_b32 v34, v4, 4, v34
	v_bitop3_b32 v4, v33, 7, v181 bitop3:0x48
	s_waitcnt vmcnt(0)
	v_bitop3_b32 v184, v162, v5, s20 bitop3:0x78
	v_and_b32_e32 v5, 0x70, v89
	v_lshl_or_b32 v38, v4, 4, v38
	v_mov_b32_e32 v17, v3
	v_bitop3_b32 v213, v162, v5, 32 bitop3:0x36
	v_bitop3_b32 v214, v162, v5, 64 bitop3:0x36
	v_bitop3_b32 v215, v162, v5, s24 bitop3:0x36
	v_lshl_add_u64 v[174:175], s[50:51], 0, v[34:35]
	v_lshl_add_u64 v[176:177], s[52:53], 0, v[38:39]
	v_mov_b32_e32 v4, v3
	v_mov_b32_e32 v5, v3
	v_mov_b32_e32 v6, v3
	v_mov_b32_e32 v7, v3
	v_mov_b32_e32 v8, v3
	v_mov_b32_e32 v9, v3
	v_mov_b32_e32 v10, v3
	v_mov_b32_e32 v11, v3
	v_mov_b32_e32 v12, v3
	v_mov_b32_e32 v13, v3
	v_mov_b32_e32 v14, v3
	v_mov_b32_e32 v15, v3
	v_mov_b64_e32 v[32:33], v[16:17]
	v_mov_b64_e32 v[48:49], v[16:17]
	v_mov_b64_e32 v[64:65], v[16:17]
	v_mov_b64_e32 v[80:81], v[16:17]
	v_add3_u32 v216, v183, v184, s22
	v_add3_u32 v217, v183, v185, s22
	v_add3_u32 v218, v183, v186, s22
	v_add3_u32 v219, v183, v187, s22
	v_add3_u32 v220, v183, v207, s22
	v_add3_u32 v221, v183, v208, s22
	v_add3_u32 v222, v183, v209, s22
	v_add3_u32 v223, v183, v210, s22
	v_mov_b64_e32 v[30:31], v[14:15]
	v_mov_b64_e32 v[28:29], v[12:13]
	v_mov_b64_e32 v[26:27], v[10:11]
	v_mov_b64_e32 v[24:25], v[8:9]
	v_mov_b64_e32 v[22:23], v[6:7]
	v_mov_b64_e32 v[20:21], v[4:5]
	v_mov_b64_e32 v[18:19], v[2:3]
	v_mov_b64_e32 v[46:47], v[14:15]
	v_mov_b64_e32 v[44:45], v[12:13]
	v_mov_b64_e32 v[42:43], v[10:11]
	v_mov_b64_e32 v[40:41], v[8:9]
	v_mov_b64_e32 v[38:39], v[6:7]
	v_mov_b64_e32 v[36:37], v[4:5]
	v_mov_b64_e32 v[34:35], v[2:3]
	v_mov_b64_e32 v[62:63], v[14:15]
	v_mov_b64_e32 v[60:61], v[12:13]
	v_mov_b64_e32 v[58:59], v[10:11]
	v_mov_b64_e32 v[56:57], v[8:9]
	v_mov_b64_e32 v[54:55], v[6:7]
	v_mov_b64_e32 v[52:53], v[4:5]
	v_mov_b64_e32 v[50:51], v[2:3]
	v_mov_b64_e32 v[78:79], v[14:15]
	v_mov_b64_e32 v[76:77], v[12:13]
	v_mov_b64_e32 v[74:75], v[10:11]
	v_mov_b64_e32 v[72:73], v[8:9]
	v_mov_b64_e32 v[70:71], v[6:7]
	v_mov_b64_e32 v[68:69], v[4:5]
	v_mov_b64_e32 v[66:67], v[2:3]
	s_waitcnt lgkmcnt(0)
	s_barrier
	v_readfirstlane_b32 s93, v181
	s_nop 3
	s_lshr_b32 s93, s93, 8
	s_cmp_eq_u32 s93, 0
	s_cbranch_scc0 .Latt_startB
; template <int VB>
; __device__ __forceinline__ void pv_tile(f32x16* o, int vb0, bf16x8 pa0, bf16x8 pa1, bf16x8 pa2, bf16x8 pa3) {
;     ...
;     PV_D0(0); PV_D0(1); PV_D0(2); PV_D0(3);
.Latt_topA:
	s_add_i32 s95, s19, 1
	s_cmp_lt_u32 s95, s57
	s_cbranch_scc0 .Latt_h1kA_ng
	s_mov_b64 s[96:97], 0x13304000
	v_lshl_add_u64 v[246:247], v[172:173], 0, s[96:97]
	s_add_i32 m0, s84, 0xe000
	s_nop 0
	global_load_lds_dwordx4 v[246:247], off
	v_lshl_add_u64 v[246:247], v[174:175], 0, s[96:97]
	s_add_i32 m0, s84, 0xe400
	s_nop 0
	global_load_lds_dwordx4 v[246:247], off
	s_mov_b64 s[96:97], 0x4d802000
	v_lshl_add_u64 v[246:247], v[176:177], 0, s[96:97]
	s_add_i32 m0, s87, 0x12000
	s_nop 0
	global_load_lds_dwordx4 v[246:247], off
.Latt_h1kA_ng:
	s_add_i32 s95, s19, 0
	s_cmp_lt_u32 s95, s57
	s_cbranch_scc0 .Latt_h1vA_ng
	s_cmp_lt_i32 s95, 1
	s_cbranch_scc1 .Latt_h1vA_ng
	s_mov_b64 s[96:97], 0x1f500000
	v_lshl_add_u64 v[246:247], v[178:179], 0, s[96:97]
	s_mov_b32 m0, s84
	s_nop 0
	global_load_lds_dwordx4 v[246:247], off
	s_mov_b64 s[96:97], 0x1f500080
	v_lshl_add_u64 v[246:247], v[178:179], 0, s[96:97]
	s_add_i32 m0, s84, 0x400
	s_nop 0
	global_load_lds_dwordx4 v[246:247], off
.Latt_h1vA_ng:
	s_cmp_lt_i32 s19, 1
	s_cbranch_scc1 .Latt_h1pA_skip
	s_add_i32 s95, s19, -1
	s_cmp_le_i32 s95, s91
	s_cselect_b64 s[96:97], -1, 0
	s_and_b64 s[96:97], s[58:59], s[96:97]
	s_andn2_b64 vcc, exec, s[96:97]
	s_cbranch_vccnz .Latt_h1pA_skip
	ds_read_b64_tr_b16 v[82:83], v163 offset:0x4000
	ds_read_b64_tr_b16 v[84:85], v163 offset:0x4800
	ds_read_b64_tr_b16 v[92:93], v163 offset:0x5000
	ds_read_b64_tr_b16 v[94:95], v163 offset:0x5800
	ds_read_b64_tr_b16 v[96:97], v163 offset:0x6000
	ds_read_b64_tr_b16 v[98:99], v163 offset:0x6800
	ds_read_b64_tr_b16 v[100:101], v163 offset:0x7000
	ds_read_b64_tr_b16 v[102:103], v163 offset:0x7800
	s_waitcnt lgkmcnt(0)
	s_nop 0
	v_mfma_f32_32x32x16_bf16 v[66:81], v[4:7], v[82:85], v[66:81]
	ds_read_b64_tr_b16 v[82:83], v163 offset:0x4200
	ds_read_b64_tr_b16 v[84:85], v163 offset:0x4a00
	v_mfma_f32_32x32x16_bf16 v[66:81], v[88:91], v[92:95], v[66:81]
	ds_read_b64_tr_b16 v[92:93], v163 offset:0x5200
	ds_read_b64_tr_b16 v[94:95], v163 offset:0x5a00
	v_mfma_f32_32x32x16_bf16 v[66:81], v[8:11], v[96:99], v[66:81]
	ds_read_b64_tr_b16 v[96:97], v163 offset:0x6200
	ds_read_b64_tr_b16 v[98:99], v163 offset:0x6a00
	v_mfma_f32_32x32x16_bf16 v[66:81], v[12:15], v[100:103], v[66:81]
	ds_read_b64_tr_b16 v[100:101], v163 offset:0x7200
	ds_read_b64_tr_b16 v[102:103], v163 offset:0x7a00
	s_waitcnt lgkmcnt(0)
	v_mfma_f32_32x32x16_bf16 v[50:65], v[4:7], v[82:85], v[50:65]
	ds_read_b64_tr_b16 v[82:83], v163 offset:0x4400
	ds_read_b64_tr_b16 v[84:85], v163 offset:0x4c00
	v_mfma_f32_32x32x16_bf16 v[50:65], v[88:91], v[92:95], v[50:65]
	ds_read_b64_tr_b16 v[92:93], v163 offset:0x5400
	ds_read_b64_tr_b16 v[94:95], v163 offset:0x5c00
	v_mfma_f32_32x32x16_bf16 v[50:65], v[8:11], v[96:99], v[50:65]
	ds_read_b64_tr_b16 v[96:97], v163 offset:0x6400
	ds_read_b64_tr_b16 v[98:99], v163 offset:0x6c00
	v_mfma_f32_32x32x16_bf16 v[50:65], v[12:15], v[100:103], v[50:65]
	ds_read_b64_tr_b16 v[100:101], v163 offset:0x7400
	ds_read_b64_tr_b16 v[102:103], v163 offset:0x7c00
	s_waitcnt lgkmcnt(0)
	v_mfma_f32_32x32x16_bf16 v[34:49], v[4:7], v[82:85], v[34:49]
	ds_read_b64_tr_b16 v[82:83], v163 offset:0x4600
	ds_read_b64_tr_b16 v[84:85], v163 offset:0x4e00
	v_mfma_f32_32x32x16_bf16 v[34:49], v[88:91], v[92:95], v[34:49]
	ds_read_b64_tr_b16 v[92:93], v163 offset:0x5600
	ds_read_b64_tr_b16 v[94:95], v163 offset:0x5e00
	v_mfma_f32_32x32x16_bf16 v[34:49], v[8:11], v[96:99], v[34:49]
	ds_read_b64_tr_b16 v[96:97], v163 offset:0x6600
	ds_read_b64_tr_b16 v[98:99], v163 offset:0x6e00
	v_mfma_f32_32x32x16_bf16 v[34:49], v[12:15], v[100:103], v[34:49]
	ds_read_b64_tr_b16 v[100:101], v163 offset:0x7600
	ds_read_b64_tr_b16 v[102:103], v163 offset:0x7e00
	s_waitcnt lgkmcnt(0)
	v_mfma_f32_32x32x16_bf16 v[18:33], v[4:7], v[82:85], v[18:33]
	v_mfma_f32_32x32x16_bf16 v[18:33], v[88:91], v[92:95], v[18:33]
	v_mfma_f32_32x32x16_bf16 v[18:33], v[8:11], v[96:99], v[18:33]
	v_mfma_f32_32x32x16_bf16 v[18:33], v[12:15], v[100:103], v[18:33]

.Latt_h1qA_skip:
	s_waitcnt lgkmcnt(0)
	s_barrier
	s_cmp_le_i32 s19, s91
	s_cselect_b64 s[96:97], -1, 0
	s_and_b64 s[96:97], s[58:59], s[96:97]
	s_andn2_b64 vcc, exec, s[96:97]
	s_cbranch_vccnz .Latt_h2sA_skip
	s_nop 10
	v_max_f32_e32 v2, v99, v99
	v_max_f32_e32 v4, v98, v98
	v_max_f32_e32 v2, v4, v2
	v_max3_f32 v2, v2, v100, v101
	v_max3_f32 v2, v2, v102, v103
	v_max3_f32 v2, v2, v104, v105
	v_max3_f32 v2, v2, v106, v107
	v_max3_f32 v2, v2, v108, v109
	v_max3_f32 v2, v2, v110, v111
	v_max3_f32 v2, v2, v112, v113
	v_max3_f32 v2, v2, v82, v83
	v_max3_f32 v2, v2, v84, v85
	v_max3_f32 v2, v2, v86, v87
	v_max3_f32 v2, v2, v88, v89
	v_max3_f32 v2, v2, v90, v91
	v_max3_f32 v2, v2, v92, v93
	v_max3_f32 v2, v2, v94, v95
	v_max3_f32 v2, v2, v96, v97
	v_mov_b32_e32 v4, v2
	s_nop 1
	v_permlane32_swap_b32_e32 v2, v4
	v_max3_f32 v2, v226, v2, v4
	v_sub_f32_e32 v4, v2, v226
	v_cmp_lt_f32_e32 vcc, s18, v4
	s_nop 1
	v_cndmask_b32_e32 v2, v226, v2, vcc
	v_sub_f32_e32 v5, v82, v2
	v_sub_f32_e32 v13, v103, v2
	v_exp_f32_e32 v8, v5
	v_sub_f32_e32 v5, v99, v2
	v_exp_f32_e32 v99, v13
	v_sub_f32_e32 v13, v87, v2
	v_sub_f32_e32 v4, v98, v2
	v_sub_f32_e32 v6, v83, v2
	v_exp_f32_e32 v14, v13
	v_sub_f32_e32 v13, v104, v2
	v_exp_f32_e32 v4, v4
	v_exp_f32_e32 v9, v6
	v_sub_f32_e32 v6, v100, v2
	v_exp_f32_e32 v100, v13
	v_sub_f32_e32 v13, v88, v2
	v_exp_f32_e32 v5, v5
	v_sub_f32_e32 v7, v84, v2
	v_exp_f32_e32 v16, v13
	v_sub_f32_e32 v13, v105, v2
	v_exp_f32_e32 v6, v6
	v_exp_f32_e32 v10, v7
	v_sub_f32_e32 v7, v101, v2
	v_sub_f32_e32 v12, v102, v2
	v_exp_f32_e32 v101, v13
	v_sub_f32_e32 v13, v89, v2
	v_exp_f32_e32 v7, v7
	v_exp_f32_e32 v98, v12
	v_sub_f32_e32 v12, v86, v2
	v_exp_f32_e32 v82, v13
	v_sub_f32_e32 v13, v106, v2
	v_sub_f32_e32 v17, v108, v2
	v_sub_f32_e32 v84, v110, v2
	v_sub_f32_e32 v86, v112, v2
	v_exp_f32_e32 v88, v13
	v_sub_f32_e32 v13, v90, v2
	v_exp_f32_e32 v90, v17
	v_sub_f32_e32 v17, v92, v2
	v_exp_f32_e32 v92, v84
	v_sub_f32_e32 v84, v94, v2
	v_exp_f32_e32 v94, v86
	v_sub_f32_e32 v86, v96, v2
	v_add_f32_e32 v96, 0, v4
	v_add_f32_e32 v96, v5, v96
	v_add_f32_e32 v96, v6, v96
	v_add_f32_e32 v96, v7, v96
	v_sub_f32_e32 v15, v107, v2
	v_add_f32_e32 v96, v98, v96
	v_exp_f32_e32 v89, v15
	v_add_f32_e32 v96, v99, v96
	v_sub_f32_e32 v83, v109, v2
	v_add_f32_e32 v96, v100, v96
	v_sub_f32_e32 v15, v91, v2
	v_exp_f32_e32 v91, v83
	v_add_f32_e32 v96, v101, v96
	v_sub_f32_e32 v11, v85, v2
	v_sub_f32_e32 v85, v111, v2
	v_add_f32_e32 v96, v88, v96
	v_sub_f32_e32 v83, v93, v2
	v_exp_f32_e32 v93, v85
	v_add_f32_e32 v96, v89, v96
	v_sub_f32_e32 v87, v113, v2
	v_add_f32_e32 v96, v90, v96
	v_sub_f32_e32 v85, v95, v2
	v_exp_f32_e32 v95, v87
	v_add_f32_e32 v96, v91, v96
	v_add_f32_e32 v96, v92, v96
	v_add_f32_e32 v96, v93, v96
	v_add_f32_e32 v96, v94, v96
	v_exp_f32_e32 v11, v11
	v_add_f32_e32 v96, v95, v96
	v_exp_f32_e32 v12, v12
	v_add_f32_e32 v96, v8, v96
	v_add_f32_e32 v96, v9, v96
	v_add_f32_e32 v96, v10, v96
	v_add_f32_e32 v96, v11, v96
	v_exp_f32_e32 v13, v13
	v_add_f32_e32 v96, v12, v96
	v_exp_f32_e32 v15, v15
	v_add_f32_e32 v96, v14, v96
	v_exp_f32_e32 v17, v17
	v_add_f32_e32 v96, v16, v96
	v_exp_f32_e32 v83, v83
	v_add_f32_e32 v96, v82, v96
	v_exp_f32_e32 v84, v84
	v_add_f32_e32 v96, v13, v96
	v_exp_f32_e32 v85, v85
	v_add_f32_e32 v96, v15, v96
	v_exp_f32_e32 v86, v86
	v_sub_f32_e32 v87, v97, v2
	v_add_f32_e32 v96, v17, v96
	v_exp_f32_e32 v87, v87
	v_add_f32_e32 v96, v83, v96
	v_add_f32_e32 v96, v84, v96
	v_add_f32_e32 v96, v85, v96
	v_sub_f32_e32 v164, v226, v2
	v_add_f32_e32 v96, v86, v96
	v_add_f32_e32 v97, v87, v96
	v_exp_f32_e32 v96, v164
	v_mov_b32_e32 v102, v97
	s_nop 1
	v_permlane32_swap_b32_e32 v97, v102
	v_cmp_gt_f32_e32 vcc, 1.0, v96
	s_cbranch_vccz .LattA_949
	s_and_saveexec_b64 s[4:5], s[2:3]
	ds_write_b32 v206, v96 offset:128
	s_or_b64 exec, exec, s[4:5]
	s_waitcnt lgkmcnt(0)
	v_add_u32_e32 v103, s90, v162
	ds_read_b128 v[104:107], v103 offset:224
	ds_read_b128 v[108:111], v103 offset:192
	ds_read_b128 v[226:229], v103 offset:160
	ds_read_b128 v[230:233], v103 offset:128
	s_waitcnt lgkmcnt(0)
	v_pk_mul_f32 v[78:79], v[78:79], v[104:105]
	v_pk_mul_f32 v[74:75], v[74:75], v[108:109]
	v_pk_mul_f32 v[70:71], v[70:71], v[226:227]
	v_pk_mul_f32 v[80:81], v[80:81], v[106:107]
	v_pk_mul_f32 v[76:77], v[76:77], v[110:111]
	v_pk_mul_f32 v[72:73], v[72:73], v[228:229]
	v_pk_mul_f32 v[68:69], v[68:69], v[232:233]
	v_pk_mul_f32 v[66:67], v[66:67], v[230:231]
	v_pk_mul_f32 v[62:63], v[62:63], v[104:105]
	v_pk_mul_f32 v[58:59], v[58:59], v[108:109]
	v_pk_mul_f32 v[54:55], v[54:55], v[226:227]
	v_pk_mul_f32 v[64:65], v[64:65], v[106:107]
	v_pk_mul_f32 v[60:61], v[60:61], v[110:111]
	v_pk_mul_f32 v[56:57], v[56:57], v[228:229]
	v_pk_mul_f32 v[52:53], v[52:53], v[232:233]
	v_pk_mul_f32 v[50:51], v[50:51], v[230:231]
	v_pk_mul_f32 v[46:47], v[46:47], v[104:105]
	v_pk_mul_f32 v[42:43], v[42:43], v[108:109]
	v_pk_mul_f32 v[38:39], v[38:39], v[226:227]
	v_pk_mul_f32 v[48:49], v[48:49], v[106:107]
	v_pk_mul_f32 v[44:45], v[44:45], v[110:111]
	v_pk_mul_f32 v[40:41], v[40:41], v[228:229]
	v_pk_mul_f32 v[36:37], v[36:37], v[232:233]
	v_pk_mul_f32 v[34:35], v[34:35], v[230:231]
	v_pk_mul_f32 v[30:31], v[30:31], v[104:105]
	v_pk_mul_f32 v[26:27], v[26:27], v[108:109]
	v_pk_mul_f32 v[22:23], v[22:23], v[226:227]
	v_pk_mul_f32 v[32:33], v[32:33], v[106:107]
	v_pk_mul_f32 v[28:29], v[28:29], v[110:111]
	v_pk_mul_f32 v[24:25], v[24:25], v[228:229]
	v_pk_mul_f32 v[20:21], v[20:21], v[232:233]
	v_pk_mul_f32 v[18:19], v[18:19], v[230:231]

; template <int VB>
; __device__ __forceinline__ void pv_tile(f32x16* o, int vb0, bf16x8 pa0, bf16x8 pa1, bf16x8 pa2, bf16x8 pa3) {
;     ...
;     PV_D0(0); PV_D0(1); PV_D0(2); PV_D0(3);
.Latt_h2sA_join:
	s_waitcnt vmcnt(0)
	s_waitcnt lgkmcnt(0)
	s_barrier
	s_add_i32 s95, s19, 2
	s_cmp_lt_u32 s95, s57
	s_cbranch_scc0 .Latt_h3kA_ng
	s_mov_b64 s[96:97], 0x13308000
	v_lshl_add_u64 v[246:247], v[172:173], 0, s[96:97]
	s_add_i32 m0, s84, 0x8000
	s_nop 0
	global_load_lds_dwordx4 v[246:247], off
	v_lshl_add_u64 v[246:247], v[174:175], 0, s[96:97]
	s_add_i32 m0, s84, 0x8400
	s_nop 0
	global_load_lds_dwordx4 v[246:247], off
	s_mov_b64 s[96:97], 0x4d804000
	v_lshl_add_u64 v[246:247], v[176:177], 0, s[96:97]
	s_add_i32 m0, s87, 0xc000
	s_nop 0
	global_load_lds_dwordx4 v[246:247], off
.Latt_h3kA_ng:
	s_add_i32 s95, s19, 1
	s_cmp_lt_u32 s95, s57
	s_cbranch_scc0 .Latt_h3vA_ng
	s_mov_b64 s[96:97], 0x1f504000
	v_lshl_add_u64 v[246:247], v[178:179], 0, s[96:97]
	s_add_i32 m0, s84, 0x4000
	s_nop 0
	global_load_lds_dwordx4 v[246:247], off
	s_mov_b64 s[96:97], 0x1f504080
	v_lshl_add_u64 v[246:247], v[178:179], 0, s[96:97]
	s_add_i32 m0, s84, 0x4400
	s_nop 0
	global_load_lds_dwordx4 v[246:247], off
.Latt_h3vA_ng:
	s_cmp_le_i32 s19, s91
	s_cselect_b64 s[96:97], -1, 0
	s_and_b64 s[96:97], s[58:59], s[96:97]
	s_andn2_b64 vcc, exec, s[96:97]
	s_cbranch_vccnz .Latt_h3pA_skip
	ds_read_b64_tr_b16 v[82:83], v163 offset:0
	ds_read_b64_tr_b16 v[84:85], v163 offset:0x800
	ds_read_b64_tr_b16 v[92:93], v163 offset:0x1000
	ds_read_b64_tr_b16 v[94:95], v163 offset:0x1800
	ds_read_b64_tr_b16 v[96:97], v163 offset:0x2000
	ds_read_b64_tr_b16 v[98:99], v163 offset:0x2800
	ds_read_b64_tr_b16 v[100:101], v163 offset:0x3000
	ds_read_b64_tr_b16 v[102:103], v163 offset:0x3800
	s_waitcnt lgkmcnt(0)
	s_nop 0
	v_mfma_f32_32x32x16_bf16 v[66:81], v[4:7], v[82:85], v[66:81]
	ds_read_b64_tr_b16 v[82:83], v163 offset:0x200
	ds_read_b64_tr_b16 v[84:85], v163 offset:0xa00
	v_mfma_f32_32x32x16_bf16 v[66:81], v[88:91], v[92:95], v[66:81]
	ds_read_b64_tr_b16 v[92:93], v163 offset:0x1200
	ds_read_b64_tr_b16 v[94:95], v163 offset:0x1a00
	v_mfma_f32_32x32x16_bf16 v[66:81], v[8:11], v[96:99], v[66:81]
	ds_read_b64_tr_b16 v[96:97], v163 offset:0x2200
	ds_read_b64_tr_b16 v[98:99], v163 offset:0x2a00
	v_mfma_f32_32x32x16_bf16 v[66:81], v[12:15], v[100:103], v[66:81]
	ds_read_b64_tr_b16 v[100:101], v163 offset:0x3200
	ds_read_b64_tr_b16 v[102:103], v163 offset:0x3a00
	s_waitcnt lgkmcnt(0)
	v_mfma_f32_32x32x16_bf16 v[50:65], v[4:7], v[82:85], v[50:65]
	ds_read_b64_tr_b16 v[82:83], v163 offset:0x400
	ds_read_b64_tr_b16 v[84:85], v163 offset:0xc00
	v_mfma_f32_32x32x16_bf16 v[50:65], v[88:91], v[92:95], v[50:65]
	ds_read_b64_tr_b16 v[92:93], v163 offset:0x1400
	ds_read_b64_tr_b16 v[94:95], v163 offset:0x1c00
	v_mfma_f32_32x32x16_bf16 v[50:65], v[8:11], v[96:99], v[50:65]
	ds_read_b64_tr_b16 v[96:97], v163 offset:0x2400
	ds_read_b64_tr_b16 v[98:99], v163 offset:0x2c00
	v_mfma_f32_32x32x16_bf16 v[50:65], v[12:15], v[100:103], v[50:65]
	ds_read_b64_tr_b16 v[100:101], v163 offset:0x3400
	ds_read_b64_tr_b16 v[102:103], v163 offset:0x3c00
	s_waitcnt lgkmcnt(0)
	v_mfma_f32_32x32x16_bf16 v[34:49], v[4:7], v[82:85], v[34:49]
	ds_read_b64_tr_b16 v[82:83], v163 offset:0x600
	ds_read_b64_tr_b16 v[84:85], v163 offset:0xe00
	v_mfma_f32_32x32x16_bf16 v[34:49], v[88:91], v[92:95], v[34:49]
	ds_read_b64_tr_b16 v[92:93], v163 offset:0x1600
	ds_read_b64_tr_b16 v[94:95], v163 offset:0x1e00
	v_mfma_f32_32x32x16_bf16 v[34:49], v[8:11], v[96:99], v[34:49]
	ds_read_b64_tr_b16 v[96:97], v163 offset:0x2600
	ds_read_b64_tr_b16 v[98:99], v163 offset:0x2e00
	v_mfma_f32_32x32x16_bf16 v[34:49], v[12:15], v[100:103], v[34:49]
	ds_read_b64_tr_b16 v[100:101], v163 offset:0x3600
	ds_read_b64_tr_b16 v[102:103], v163 offset:0x3e00
	s_waitcnt lgkmcnt(0)
	v_mfma_f32_32x32x16_bf16 v[18:33], v[4:7], v[82:85], v[18:33]
	v_mfma_f32_32x32x16_bf16 v[18:33], v[88:91], v[92:95], v[18:33]
	v_mfma_f32_32x32x16_bf16 v[18:33], v[8:11], v[96:99], v[18:33]
	v_mfma_f32_32x32x16_bf16 v[18:33], v[12:15], v[100:103], v[18:33]

.Latt_h3qA_skip:
	s_waitcnt lgkmcnt(0)
	s_barrier
	s_add_i32 s95, s19, 1
	s_cmp_le_i32 s95, s91
	s_cselect_b64 s[96:97], -1, 0
	s_and_b64 s[96:97], s[58:59], s[96:97]
	s_andn2_b64 vcc, exec, s[96:97]
	s_cbranch_vccnz .Latt_h4sA_skip
	s_nop 10
	v_max_f32_e32 v4, v83, v83
	v_max_f32_e32 v5, v82, v82
	v_max_f32_e32 v4, v5, v4
	v_max3_f32 v4, v4, v84, v85
	v_max3_f32 v4, v4, v86, v87
	v_max3_f32 v4, v4, v88, v89
	v_max3_f32 v4, v4, v90, v91
	v_max3_f32 v4, v4, v92, v93
	v_max3_f32 v4, v4, v94, v95
	v_max3_f32 v4, v4, v96, v97
	v_max3_f32 v4, v4, v98, v99
	v_max3_f32 v4, v4, v100, v101
	v_max3_f32 v4, v4, v102, v103
	v_max3_f32 v4, v4, v104, v105
	v_max3_f32 v4, v4, v106, v107
	v_max3_f32 v4, v4, v108, v109
	v_max3_f32 v4, v4, v110, v111
	v_max3_f32 v4, v4, v112, v113
	v_mov_b32_e32 v5, v4
	s_nop 1
	v_permlane32_swap_b32_e32 v4, v5
	v_max3_f32 v4, v2, v4, v5
	v_sub_f32_e32 v5, v4, v2
	v_cmp_lt_f32_e32 vcc, s18, v5
	s_nop 1
	v_cndmask_b32_e32 v226, v2, v4, vcc
	v_sub_f32_e32 v164, v2, v226
	v_sub_f32_e32 v2, v82, v226
	v_exp_f32_e32 v4, v2
	v_sub_f32_e32 v5, v83, v226
	v_sub_f32_e32 v6, v99, v226
	v_exp_f32_e32 v5, v5
	v_exp_f32_e32 v8, v6
	v_sub_f32_e32 v6, v84, v226
	v_sub_f32_e32 v7, v100, v226
	v_sub_f32_e32 v12, v87, v226
	v_exp_f32_e32 v6, v6
	v_exp_f32_e32 v9, v7
	v_sub_f32_e32 v7, v85, v226
	v_exp_f32_e32 v99, v12
	v_sub_f32_e32 v12, v103, v226
	v_exp_f32_e32 v7, v7
	v_sub_f32_e32 v11, v86, v226
	v_exp_f32_e32 v13, v12
	v_sub_f32_e32 v12, v88, v226
	v_sub_f32_e32 v2, v98, v226
	v_exp_f32_e32 v98, v11
	v_exp_f32_e32 v100, v12
	v_sub_f32_e32 v12, v104, v226
	v_sub_f32_e32 v84, v95, v226
	v_add_f32_e32 v95, 0, v4
	v_exp_f32_e32 v15, v12
	v_sub_f32_e32 v12, v89, v226
	v_add_f32_e32 v95, v5, v95
	v_sub_f32_e32 v10, v101, v226
	v_exp_f32_e32 v101, v12
	v_sub_f32_e32 v12, v105, v226
	v_add_f32_e32 v95, v6, v95
	v_exp_f32_e32 v17, v12
	v_sub_f32_e32 v12, v90, v226
	v_add_f32_e32 v95, v7, v95
	v_exp_f32_e32 v87, v12
	v_sub_f32_e32 v14, v91, v226
	v_add_f32_e32 v95, v98, v95
	v_exp_f32_e32 v88, v14
	v_sub_f32_e32 v16, v92, v226
	v_add_f32_e32 v95, v99, v95
	v_exp_f32_e32 v89, v16
	v_sub_f32_e32 v82, v93, v226
	v_add_f32_e32 v95, v100, v95
	v_exp_f32_e32 v90, v82
	v_sub_f32_e32 v83, v94, v226
	v_add_f32_e32 v95, v101, v95
	v_exp_f32_e32 v91, v83
	v_add_f32_e32 v95, v87, v95
	v_exp_f32_e32 v92, v84
	v_sub_f32_e32 v85, v96, v226
	v_add_f32_e32 v95, v88, v95
	v_exp_f32_e32 v93, v85
	v_sub_f32_e32 v86, v97, v226
	v_add_f32_e32 v95, v89, v95
	v_exp_f32_e32 v94, v86
	v_add_f32_e32 v95, v90, v95
	v_exp_f32_e32 v2, v2
	v_add_f32_e32 v95, v91, v95
	v_add_f32_e32 v95, v92, v95
	v_add_f32_e32 v95, v93, v95
	v_exp_f32_e32 v10, v10
	v_sub_f32_e32 v11, v102, v226
	v_add_f32_e32 v95, v94, v95
	v_exp_f32_e32 v11, v11
	v_add_f32_e32 v95, v2, v95
	v_add_f32_e32 v95, v8, v95
	v_add_f32_e32 v95, v9, v95
	v_sub_f32_e32 v12, v106, v226
	v_add_f32_e32 v95, v10, v95
	v_exp_f32_e32 v12, v12
	v_sub_f32_e32 v14, v107, v226
	v_add_f32_e32 v95, v11, v95
	v_exp_f32_e32 v14, v14
	v_sub_f32_e32 v16, v108, v226
	v_add_f32_e32 v95, v13, v95
	v_exp_f32_e32 v16, v16
	v_sub_f32_e32 v82, v109, v226
	v_add_f32_e32 v95, v15, v95
	v_exp_f32_e32 v82, v82
	v_sub_f32_e32 v83, v110, v226
	v_add_f32_e32 v95, v17, v95
	v_exp_f32_e32 v83, v83
	v_sub_f32_e32 v84, v111, v226
	v_add_f32_e32 v95, v12, v95
	v_exp_f32_e32 v84, v84
	v_sub_f32_e32 v85, v112, v226
	v_add_f32_e32 v95, v14, v95
	v_exp_f32_e32 v85, v85
	v_sub_f32_e32 v86, v113, v226
	v_add_f32_e32 v95, v16, v95
	v_exp_f32_e32 v86, v86
	v_add_f32_e32 v95, v82, v95
	v_add_f32_e32 v95, v83, v95
	v_add_f32_e32 v95, v84, v95
	v_add_f32_e32 v95, v85, v95
	v_add_f32_e32 v96, v86, v95
	v_exp_f32_e32 v95, v164
	v_mov_b32_e32 v97, v96
	s_nop 1
	v_permlane32_swap_b32_e32 v96, v97
	v_cmp_gt_f32_e32 vcc, 1.0, v95
	s_cbranch_vccz .LattA_960
	s_and_saveexec_b64 s[60:61], s[2:3]
	ds_write_b32 v206, v95 offset:128
	s_or_b64 exec, exec, s[60:61]
	s_waitcnt lgkmcnt(0)
	v_add_u32_e32 v164, s90, v162
	ds_read_b128 v[102:105], v164 offset:224
	ds_read_b128 v[106:109], v164 offset:192
	ds_read_b128 v[110:113], v164 offset:160
	ds_read_b128 v[228:231], v164 offset:128
	s_waitcnt lgkmcnt(0)
	v_pk_mul_f32 v[78:79], v[78:79], v[102:103]
	v_pk_mul_f32 v[74:75], v[74:75], v[106:107]
	v_pk_mul_f32 v[70:71], v[70:71], v[110:111]
	v_pk_mul_f32 v[80:81], v[80:81], v[104:105]
	v_pk_mul_f32 v[76:77], v[76:77], v[108:109]
	v_pk_mul_f32 v[72:73], v[72:73], v[112:113]
	v_pk_mul_f32 v[68:69], v[68:69], v[230:231]
	v_pk_mul_f32 v[66:67], v[66:67], v[228:229]
	v_pk_mul_f32 v[62:63], v[62:63], v[102:103]
	v_pk_mul_f32 v[58:59], v[58:59], v[106:107]
	v_pk_mul_f32 v[54:55], v[54:55], v[110:111]
	v_pk_mul_f32 v[64:65], v[64:65], v[104:105]
	v_pk_mul_f32 v[60:61], v[60:61], v[108:109]
	v_pk_mul_f32 v[56:57], v[56:57], v[112:113]
	v_pk_mul_f32 v[52:53], v[52:53], v[230:231]
	v_pk_mul_f32 v[50:51], v[50:51], v[228:229]
	v_pk_mul_f32 v[46:47], v[46:47], v[102:103]
	v_pk_mul_f32 v[42:43], v[42:43], v[106:107]
	v_pk_mul_f32 v[38:39], v[38:39], v[110:111]
	v_pk_mul_f32 v[48:49], v[48:49], v[104:105]
	v_pk_mul_f32 v[44:45], v[44:45], v[108:109]
	v_pk_mul_f32 v[40:41], v[40:41], v[112:113]
	v_pk_mul_f32 v[36:37], v[36:37], v[230:231]
	v_pk_mul_f32 v[34:35], v[34:35], v[228:229]
	v_pk_mul_f32 v[30:31], v[30:31], v[102:103]
	v_pk_mul_f32 v[26:27], v[26:27], v[106:107]
	v_pk_mul_f32 v[22:23], v[22:23], v[110:111]
	v_pk_mul_f32 v[32:33], v[32:33], v[104:105]
	v_pk_mul_f32 v[28:29], v[28:29], v[108:109]
	v_pk_mul_f32 v[24:25], v[24:25], v[112:113]
	v_pk_mul_f32 v[20:21], v[20:21], v[230:231]
	v_pk_mul_f32 v[18:19], v[18:19], v[228:229]

; template <int VB>
; __device__ __forceinline__ void pv_tile(f32x16* o, int vb0, bf16x8 pa0, bf16x8 pa1, bf16x8 pa2, bf16x8 pa3) {
;     ...
;     PV_D0(0); PV_D0(1); PV_D0(2); PV_D0(3);
; template <int VAR>
; __device__ __forceinline__ void attn_unit(const AUnit& u, LAS char* lds) {
;     ...
;     for (int j = 0; j < u.nt; j += 2) {
;         ASTEP(0, j);
;         if (j + 1 < u.nt) ASTEP(1, j + 1);
;     }
.Latt_h4sA_join:
	s_waitcnt vmcnt(0)
	s_waitcnt lgkmcnt(0)
	s_barrier
	v_lshl_add_u64 v[172:173], v[172:173], 0, s[26:27]
	v_lshl_add_u64 v[174:175], v[174:175], 0, s[26:27]
	v_lshl_add_u64 v[176:177], v[176:177], 0, s[16:17]
	v_lshl_add_u64 v[178:179], v[178:179], 0, s[26:27]
	s_add_i32 s19, s19, 2
	s_cmp_ge_u32 s19, s57
	s_cbranch_scc0 .Latt_topA
	s_add_i32 s95, s19, -1
	s_cmp_le_i32 s95, s91
	s_cselect_b64 s[96:97], -1, 0
	s_and_b64 s[96:97], s[58:59], s[96:97]
	s_andn2_b64 vcc, exec, s[96:97]
	s_cbranch_vccnz .Latt_h5pA_skip
	ds_read_b64_tr_b16 v[82:83], v163 offset:0x4000
	ds_read_b64_tr_b16 v[84:85], v163 offset:0x4800
	ds_read_b64_tr_b16 v[92:93], v163 offset:0x5000
	ds_read_b64_tr_b16 v[94:95], v163 offset:0x5800
	ds_read_b64_tr_b16 v[96:97], v163 offset:0x6000
	ds_read_b64_tr_b16 v[98:99], v163 offset:0x6800
	ds_read_b64_tr_b16 v[100:101], v163 offset:0x7000
	ds_read_b64_tr_b16 v[102:103], v163 offset:0x7800
	s_waitcnt lgkmcnt(0)
	s_nop 0
	v_mfma_f32_32x32x16_bf16 v[66:81], v[4:7], v[82:85], v[66:81]
	ds_read_b64_tr_b16 v[82:83], v163 offset:0x4200
	ds_read_b64_tr_b16 v[84:85], v163 offset:0x4a00
	v_mfma_f32_32x32x16_bf16 v[66:81], v[88:91], v[92:95], v[66:81]
	ds_read_b64_tr_b16 v[92:93], v163 offset:0x5200
	ds_read_b64_tr_b16 v[94:95], v163 offset:0x5a00
	v_mfma_f32_32x32x16_bf16 v[66:81], v[8:11], v[96:99], v[66:81]
	ds_read_b64_tr_b16 v[96:97], v163 offset:0x6200
	ds_read_b64_tr_b16 v[98:99], v163 offset:0x6a00
	v_mfma_f32_32x32x16_bf16 v[66:81], v[12:15], v[100:103], v[66:81]
	ds_read_b64_tr_b16 v[100:101], v163 offset:0x7200
	ds_read_b64_tr_b16 v[102:103], v163 offset:0x7a00
	s_waitcnt lgkmcnt(0)
	v_mfma_f32_32x32x16_bf16 v[50:65], v[4:7], v[82:85], v[50:65]
	ds_read_b64_tr_b16 v[82:83], v163 offset:0x4400
	ds_read_b64_tr_b16 v[84:85], v163 offset:0x4c00
	v_mfma_f32_32x32x16_bf16 v[50:65], v[88:91], v[92:95], v[50:65]
	ds_read_b64_tr_b16 v[92:93], v163 offset:0x5400
	ds_read_b64_tr_b16 v[94:95], v163 offset:0x5c00
	v_mfma_f32_32x32x16_bf16 v[50:65], v[8:11], v[96:99], v[50:65]
	ds_read_b64_tr_b16 v[96:97], v163 offset:0x6400
	ds_read_b64_tr_b16 v[98:99], v163 offset:0x6c00
	v_mfma_f32_32x32x16_bf16 v[50:65], v[12:15], v[100:103], v[50:65]
	ds_read_b64_tr_b16 v[100:101], v163 offset:0x7400
	ds_read_b64_tr_b16 v[102:103], v163 offset:0x7c00
	s_waitcnt lgkmcnt(0)
	v_mfma_f32_32x32x16_bf16 v[34:49], v[4:7], v[82:85], v[34:49]
	ds_read_b64_tr_b16 v[82:83], v163 offset:0x4600
	ds_read_b64_tr_b16 v[84:85], v163 offset:0x4e00
	v_mfma_f32_32x32x16_bf16 v[34:49], v[88:91], v[92:95], v[34:49]
	ds_read_b64_tr_b16 v[92:93], v163 offset:0x5600
	ds_read_b64_tr_b16 v[94:95], v163 offset:0x5e00
	v_mfma_f32_32x32x16_bf16 v[34:49], v[8:11], v[96:99], v[34:49]
	ds_read_b64_tr_b16 v[96:97], v163 offset:0x6600
	ds_read_b64_tr_b16 v[98:99], v163 offset:0x6e00
	v_mfma_f32_32x32x16_bf16 v[34:49], v[12:15], v[100:103], v[34:49]
	ds_read_b64_tr_b16 v[100:101], v163 offset:0x7600
	ds_read_b64_tr_b16 v[102:103], v163 offset:0x7e00
	s_waitcnt lgkmcnt(0)
	v_mfma_f32_32x32x16_bf16 v[18:33], v[4:7], v[82:85], v[18:33]
	v_mfma_f32_32x32x16_bf16 v[18:33], v[88:91], v[92:95], v[18:33]
	v_mfma_f32_32x32x16_bf16 v[18:33], v[8:11], v[96:99], v[18:33]
	v_mfma_f32_32x32x16_bf16 v[18:33], v[12:15], v[100:103], v[18:33]
.Latt_h5pA_skip:
	s_waitcnt vmcnt(0)
	s_waitcnt lgkmcnt(0)
	s_barrier
	s_barrier
	s_branch .Latt_exit
.Latt_startB:
	s_mov_b64 s[96:97], 0x13304000
	v_lshl_add_u64 v[246:247], v[172:173], 0, s[96:97]
	s_add_i32 m0, s84, 0xe000
	s_nop 0
	global_load_lds_dwordx4 v[246:247], off
	v_lshl_add_u64 v[246:247], v[174:175], 0, s[96:97]
	s_add_i32 m0, s84, 0xe400
	s_nop 0
	global_load_lds_dwordx4 v[246:247], off
	s_mov_b64 s[96:97], 0x4d802000
	v_lshl_add_u64 v[246:247], v[176:177], 0, s[96:97]
	s_add_i32 m0, s87, 0x12000
	s_nop 0
	global_load_lds_dwordx4 v[246:247], off
	s_barrier

.Latt_h2kB_ng:
	s_add_i32 s95, s19, 1
	s_cmp_lt_u32 s95, s57
	s_cbranch_scc0 .Latt_h2vB_ng
	s_mov_b64 s[96:97], 0x1f504000
	v_lshl_add_u64 v[246:247], v[178:179], 0, s[96:97]
	s_add_i32 m0, s84, 0x4000
	s_nop 0
	global_load_lds_dwordx4 v[246:247], off
	s_mov_b64 s[96:97], 0x1f504080
	v_lshl_add_u64 v[246:247], v[178:179], 0, s[96:97]
	s_add_i32 m0, s84, 0x4400
	s_nop 0
	global_load_lds_dwordx4 v[246:247], off
.Latt_h2vB_ng:
	s_cmp_le_i32 s19, s91
	s_cselect_b64 s[96:97], -1, 0
	s_and_b64 s[96:97], s[58:59], s[96:97]
	s_andn2_b64 vcc, exec, s[96:97]
	s_cbranch_vccnz .Latt_h2sB_skip
	s_nop 10
	v_max_f32_e32 v2, v99, v99
	v_max_f32_e32 v4, v98, v98
	v_max_f32_e32 v2, v4, v2
	v_max3_f32 v2, v2, v100, v101
	v_max3_f32 v2, v2, v102, v103
	v_max3_f32 v2, v2, v104, v105
	v_max3_f32 v2, v2, v106, v107
	v_max3_f32 v2, v2, v108, v109
	v_max3_f32 v2, v2, v110, v111
	v_max3_f32 v2, v2, v112, v113
	v_max3_f32 v2, v2, v82, v83
	v_max3_f32 v2, v2, v84, v85
	v_max3_f32 v2, v2, v86, v87
	v_max3_f32 v2, v2, v88, v89
	v_max3_f32 v2, v2, v90, v91
	v_max3_f32 v2, v2, v92, v93
	v_max3_f32 v2, v2, v94, v95
	v_max3_f32 v2, v2, v96, v97
	v_mov_b32_e32 v4, v2
	s_nop 1
	v_permlane32_swap_b32_e32 v2, v4
	v_max3_f32 v2, v226, v2, v4
	v_sub_f32_e32 v4, v2, v226
	v_cmp_lt_f32_e32 vcc, s18, v4
	s_nop 1
	v_cndmask_b32_e32 v2, v226, v2, vcc
	v_sub_f32_e32 v5, v82, v2
	v_sub_f32_e32 v13, v103, v2
	v_exp_f32_e32 v8, v5
	v_sub_f32_e32 v5, v99, v2
	v_exp_f32_e32 v99, v13
	v_sub_f32_e32 v13, v87, v2
	v_sub_f32_e32 v4, v98, v2
	v_sub_f32_e32 v6, v83, v2
	v_exp_f32_e32 v14, v13
	v_sub_f32_e32 v13, v104, v2
	v_exp_f32_e32 v4, v4
	v_exp_f32_e32 v9, v6
	v_sub_f32_e32 v6, v100, v2
	v_exp_f32_e32 v100, v13
	v_sub_f32_e32 v13, v88, v2
	v_exp_f32_e32 v5, v5
	v_sub_f32_e32 v7, v84, v2
	v_exp_f32_e32 v16, v13
	v_sub_f32_e32 v13, v105, v2
	v_exp_f32_e32 v6, v6
	v_exp_f32_e32 v10, v7
	v_sub_f32_e32 v7, v101, v2
	v_sub_f32_e32 v12, v102, v2
	v_exp_f32_e32 v101, v13
	v_sub_f32_e32 v13, v89, v2
	v_exp_f32_e32 v7, v7
	v_exp_f32_e32 v98, v12
	v_sub_f32_e32 v12, v86, v2
	v_exp_f32_e32 v82, v13
	v_sub_f32_e32 v13, v106, v2
	v_sub_f32_e32 v17, v108, v2
	v_sub_f32_e32 v84, v110, v2
	v_sub_f32_e32 v86, v112, v2
	v_exp_f32_e32 v88, v13
	v_sub_f32_e32 v13, v90, v2
	v_exp_f32_e32 v90, v17
	v_sub_f32_e32 v17, v92, v2
	v_exp_f32_e32 v92, v84
	v_sub_f32_e32 v84, v94, v2
	v_exp_f32_e32 v94, v86
	v_sub_f32_e32 v86, v96, v2
	v_add_f32_e32 v96, 0, v4
	v_add_f32_e32 v96, v5, v96
	v_add_f32_e32 v96, v6, v96
	v_add_f32_e32 v96, v7, v96
	v_sub_f32_e32 v15, v107, v2
	v_add_f32_e32 v96, v98, v96
	v_exp_f32_e32 v89, v15
	v_add_f32_e32 v96, v99, v96
	v_sub_f32_e32 v83, v109, v2
	v_add_f32_e32 v96, v100, v96
	v_sub_f32_e32 v15, v91, v2
	v_exp_f32_e32 v91, v83
	v_add_f32_e32 v96, v101, v96
	v_sub_f32_e32 v11, v85, v2
	v_sub_f32_e32 v85, v111, v2
	v_add_f32_e32 v96, v88, v96
	v_sub_f32_e32 v83, v93, v2
	v_exp_f32_e32 v93, v85
	v_add_f32_e32 v96, v89, v96
	v_sub_f32_e32 v87, v113, v2
	v_add_f32_e32 v96, v90, v96
	v_sub_f32_e32 v85, v95, v2
	v_exp_f32_e32 v95, v87
	v_add_f32_e32 v96, v91, v96
	v_add_f32_e32 v96, v92, v96
	v_add_f32_e32 v96, v93, v96
	v_add_f32_e32 v96, v94, v96
	v_exp_f32_e32 v11, v11
	v_add_f32_e32 v96, v95, v96
	v_exp_f32_e32 v12, v12
	v_add_f32_e32 v96, v8, v96
	v_add_f32_e32 v96, v9, v96
	v_add_f32_e32 v96, v10, v96
	v_add_f32_e32 v96, v11, v96
	v_exp_f32_e32 v13, v13
	v_add_f32_e32 v96, v12, v96
	v_exp_f32_e32 v15, v15
	v_add_f32_e32 v96, v14, v96
	v_exp_f32_e32 v17, v17
	v_add_f32_e32 v96, v16, v96
	v_exp_f32_e32 v83, v83
	v_add_f32_e32 v96, v82, v96
	v_exp_f32_e32 v84, v84
	v_add_f32_e32 v96, v13, v96
	v_exp_f32_e32 v85, v85
	v_add_f32_e32 v96, v15, v96
	v_exp_f32_e32 v86, v86
	v_sub_f32_e32 v87, v97, v2
	v_add_f32_e32 v96, v17, v96
	v_exp_f32_e32 v87, v87
	v_add_f32_e32 v96, v83, v96
	v_add_f32_e32 v96, v84, v96
	v_add_f32_e32 v96, v85, v96
	v_sub_f32_e32 v164, v226, v2
	v_add_f32_e32 v96, v86, v96
	v_add_f32_e32 v97, v87, v96
	v_exp_f32_e32 v96, v164
	v_mov_b32_e32 v102, v97
	s_nop 1
	v_permlane32_swap_b32_e32 v97, v102
	v_cmp_gt_f32_e32 vcc, 1.0, v96
	s_cbranch_vccz .LattB_949
	s_and_saveexec_b64 s[4:5], s[2:3]
	ds_write_b32 v206, v96 offset:128
	s_or_b64 exec, exec, s[4:5]
	s_waitcnt lgkmcnt(0)
	v_add_u32_e32 v103, s90, v162
	ds_read_b128 v[104:107], v103 offset:224
	ds_read_b128 v[108:111], v103 offset:192
	ds_read_b128 v[226:229], v103 offset:160
	ds_read_b128 v[230:233], v103 offset:128
	s_waitcnt lgkmcnt(0)
	v_pk_mul_f32 v[78:79], v[78:79], v[104:105]
	v_pk_mul_f32 v[74:75], v[74:75], v[108:109]
	v_pk_mul_f32 v[70:71], v[70:71], v[226:227]
	v_pk_mul_f32 v[80:81], v[80:81], v[106:107]
	v_pk_mul_f32 v[76:77], v[76:77], v[110:111]
	v_pk_mul_f32 v[72:73], v[72:73], v[228:229]
	v_pk_mul_f32 v[68:69], v[68:69], v[232:233]
	v_pk_mul_f32 v[66:67], v[66:67], v[230:231]
	v_pk_mul_f32 v[62:63], v[62:63], v[104:105]
	v_pk_mul_f32 v[58:59], v[58:59], v[108:109]
	v_pk_mul_f32 v[54:55], v[54:55], v[226:227]
	v_pk_mul_f32 v[64:65], v[64:65], v[106:107]
	v_pk_mul_f32 v[60:61], v[60:61], v[110:111]
	v_pk_mul_f32 v[56:57], v[56:57], v[228:229]
	v_pk_mul_f32 v[52:53], v[52:53], v[232:233]
	v_pk_mul_f32 v[50:51], v[50:51], v[230:231]
	v_pk_mul_f32 v[46:47], v[46:47], v[104:105]
	v_pk_mul_f32 v[42:43], v[42:43], v[108:109]
	v_pk_mul_f32 v[38:39], v[38:39], v[226:227]
	v_pk_mul_f32 v[48:49], v[48:49], v[106:107]
	v_pk_mul_f32 v[44:45], v[44:45], v[110:111]
	v_pk_mul_f32 v[40:41], v[40:41], v[228:229]
	v_pk_mul_f32 v[36:37], v[36:37], v[232:233]
	v_pk_mul_f32 v[34:35], v[34:35], v[230:231]
	v_pk_mul_f32 v[30:31], v[30:31], v[104:105]
	v_pk_mul_f32 v[26:27], v[26:27], v[108:109]
	v_pk_mul_f32 v[22:23], v[22:23], v[226:227]
	v_pk_mul_f32 v[32:33], v[32:33], v[106:107]
	v_pk_mul_f32 v[28:29], v[28:29], v[110:111]
	v_pk_mul_f32 v[24:25], v[24:25], v[228:229]
	v_pk_mul_f32 v[20:21], v[20:21], v[232:233]
	v_pk_mul_f32 v[18:19], v[18:19], v[230:231]

; template <int VB>
; __device__ __forceinline__ void pv_tile(f32x16* o, int vb0, bf16x8 pa0, bf16x8 pa1, bf16x8 pa2, bf16x8 pa3) {
;     ...
;     PV_D0(0); PV_D0(1); PV_D0(2); PV_D0(3);
.Latt_h2sB_join:
	s_waitcnt lgkmcnt(0)
	s_barrier
	s_cmp_le_i32 s19, s91
	s_cselect_b64 s[96:97], -1, 0
	s_and_b64 s[96:97], s[58:59], s[96:97]
	s_andn2_b64 vcc, exec, s[96:97]
	s_cbranch_vccnz .Latt_h3pB_skip
	ds_read_b64_tr_b16 v[82:83], v163 offset:0
	ds_read_b64_tr_b16 v[84:85], v163 offset:0x800
	ds_read_b64_tr_b16 v[92:93], v163 offset:0x1000
	ds_read_b64_tr_b16 v[94:95], v163 offset:0x1800
	ds_read_b64_tr_b16 v[96:97], v163 offset:0x2000
	ds_read_b64_tr_b16 v[98:99], v163 offset:0x2800
	ds_read_b64_tr_b16 v[100:101], v163 offset:0x3000
	ds_read_b64_tr_b16 v[102:103], v163 offset:0x3800
	s_waitcnt lgkmcnt(0)
	s_nop 0
	v_mfma_f32_32x32x16_bf16 v[66:81], v[4:7], v[82:85], v[66:81]
	ds_read_b64_tr_b16 v[82:83], v163 offset:0x200
	ds_read_b64_tr_b16 v[84:85], v163 offset:0xa00
	v_mfma_f32_32x32x16_bf16 v[66:81], v[88:91], v[92:95], v[66:81]
	ds_read_b64_tr_b16 v[92:93], v163 offset:0x1200
	ds_read_b64_tr_b16 v[94:95], v163 offset:0x1a00
	v_mfma_f32_32x32x16_bf16 v[66:81], v[8:11], v[96:99], v[66:81]
	ds_read_b64_tr_b16 v[96:97], v163 offset:0x2200
	ds_read_b64_tr_b16 v[98:99], v163 offset:0x2a00
	v_mfma_f32_32x32x16_bf16 v[66:81], v[12:15], v[100:103], v[66:81]
	ds_read_b64_tr_b16 v[100:101], v163 offset:0x3200
	ds_read_b64_tr_b16 v[102:103], v163 offset:0x3a00
	s_waitcnt lgkmcnt(0)
	v_mfma_f32_32x32x16_bf16 v[50:65], v[4:7], v[82:85], v[50:65]
	ds_read_b64_tr_b16 v[82:83], v163 offset:0x400
	ds_read_b64_tr_b16 v[84:85], v163 offset:0xc00
	v_mfma_f32_32x32x16_bf16 v[50:65], v[88:91], v[92:95], v[50:65]
	ds_read_b64_tr_b16 v[92:93], v163 offset:0x1400
	ds_read_b64_tr_b16 v[94:95], v163 offset:0x1c00
	v_mfma_f32_32x32x16_bf16 v[50:65], v[8:11], v[96:99], v[50:65]
	ds_read_b64_tr_b16 v[96:97], v163 offset:0x2400
	ds_read_b64_tr_b16 v[98:99], v163 offset:0x2c00
	v_mfma_f32_32x32x16_bf16 v[50:65], v[12:15], v[100:103], v[50:65]
	ds_read_b64_tr_b16 v[100:101], v163 offset:0x3400
	ds_read_b64_tr_b16 v[102:103], v163 offset:0x3c00
	s_waitcnt lgkmcnt(0)
	v_mfma_f32_32x32x16_bf16 v[34:49], v[4:7], v[82:85], v[34:49]
	ds_read_b64_tr_b16 v[82:83], v163 offset:0x600
	ds_read_b64_tr_b16 v[84:85], v163 offset:0xe00
	v_mfma_f32_32x32x16_bf16 v[34:49], v[88:91], v[92:95], v[34:49]
	ds_read_b64_tr_b16 v[92:93], v163 offset:0x1600
	ds_read_b64_tr_b16 v[94:95], v163 offset:0x1e00
	v_mfma_f32_32x32x16_bf16 v[34:49], v[8:11], v[96:99], v[34:49]
	ds_read_b64_tr_b16 v[96:97], v163 offset:0x2600
	ds_read_b64_tr_b16 v[98:99], v163 offset:0x2e00
	v_mfma_f32_32x32x16_bf16 v[34:49], v[12:15], v[100:103], v[34:49]
	ds_read_b64_tr_b16 v[100:101], v163 offset:0x3600
	ds_read_b64_tr_b16 v[102:103], v163 offset:0x3e00
	s_waitcnt lgkmcnt(0)
	v_mfma_f32_32x32x16_bf16 v[18:33], v[4:7], v[82:85], v[18:33]
	v_mfma_f32_32x32x16_bf16 v[18:33], v[88:91], v[92:95], v[18:33]
	v_mfma_f32_32x32x16_bf16 v[18:33], v[8:11], v[96:99], v[18:33]
	v_mfma_f32_32x32x16_bf16 v[18:33], v[12:15], v[100:103], v[18:33]

.Latt_h3qB_skip:
	s_waitcnt vmcnt(0)
	s_waitcnt lgkmcnt(0)
	s_barrier
	s_add_i32 s95, s19, 3
	s_cmp_lt_u32 s95, s57
	s_cbranch_scc0 .Latt_h4kB_ng
	s_mov_b64 s[96:97], 0x1330c000
	v_lshl_add_u64 v[246:247], v[172:173], 0, s[96:97]
	s_add_i32 m0, s84, 0xe000
	s_nop 0
	global_load_lds_dwordx4 v[246:247], off
	v_lshl_add_u64 v[246:247], v[174:175], 0, s[96:97]
	s_add_i32 m0, s84, 0xe400
	s_nop 0
	global_load_lds_dwordx4 v[246:247], off
	s_mov_b64 s[96:97], 0x4d806000
	v_lshl_add_u64 v[246:247], v[176:177], 0, s[96:97]
	s_add_i32 m0, s87, 0x12000
	s_nop 0
	global_load_lds_dwordx4 v[246:247], off
.Latt_h4kB_ng:
	s_add_i32 s95, s19, 2
	s_cmp_lt_u32 s95, s57
	s_cbranch_scc0 .Latt_h4vB_ng
	s_mov_b64 s[96:97], 0x1f508000
	v_lshl_add_u64 v[246:247], v[178:179], 0, s[96:97]
	s_mov_b32 m0, s84
	s_nop 0
	global_load_lds_dwordx4 v[246:247], off
	s_mov_b64 s[96:97], 0x1f508080
	v_lshl_add_u64 v[246:247], v[178:179], 0, s[96:97]
	s_add_i32 m0, s84, 0x400
	s_nop 0
	global_load_lds_dwordx4 v[246:247], off
.Latt_h4vB_ng:
	s_add_i32 s95, s19, 1
	s_cmp_le_i32 s95, s91
	s_cselect_b64 s[96:97], -1, 0
	s_and_b64 s[96:97], s[58:59], s[96:97]
	s_andn2_b64 vcc, exec, s[96:97]
	s_cbranch_vccnz .Latt_h4sB_skip
	s_nop 10
	v_max_f32_e32 v4, v83, v83
	v_max_f32_e32 v5, v82, v82
	v_max_f32_e32 v4, v5, v4
	v_max3_f32 v4, v4, v84, v85
	v_max3_f32 v4, v4, v86, v87
	v_max3_f32 v4, v4, v88, v89
	v_max3_f32 v4, v4, v90, v91
	v_max3_f32 v4, v4, v92, v93
	v_max3_f32 v4, v4, v94, v95
	v_max3_f32 v4, v4, v96, v97
	v_max3_f32 v4, v4, v98, v99
	v_max3_f32 v4, v4, v100, v101
	v_max3_f32 v4, v4, v102, v103
	v_max3_f32 v4, v4, v104, v105
	v_max3_f32 v4, v4, v106, v107
	v_max3_f32 v4, v4, v108, v109
	v_max3_f32 v4, v4, v110, v111
	v_max3_f32 v4, v4, v112, v113
	v_mov_b32_e32 v5, v4
	s_nop 1
	v_permlane32_swap_b32_e32 v4, v5
	v_max3_f32 v4, v2, v4, v5
	v_sub_f32_e32 v5, v4, v2
	v_cmp_lt_f32_e32 vcc, s18, v5
	s_nop 1
	v_cndmask_b32_e32 v226, v2, v4, vcc
	v_sub_f32_e32 v164, v2, v226
	v_sub_f32_e32 v2, v82, v226
	v_exp_f32_e32 v4, v2
	v_sub_f32_e32 v5, v83, v226
	v_sub_f32_e32 v6, v99, v226
	v_exp_f32_e32 v5, v5
	v_exp_f32_e32 v8, v6
	v_sub_f32_e32 v6, v84, v226
	v_sub_f32_e32 v7, v100, v226
	v_sub_f32_e32 v12, v87, v226
	v_exp_f32_e32 v6, v6
	v_exp_f32_e32 v9, v7
	v_sub_f32_e32 v7, v85, v226
	v_exp_f32_e32 v99, v12
	v_sub_f32_e32 v12, v103, v226
	v_exp_f32_e32 v7, v7
	v_sub_f32_e32 v11, v86, v226
	v_exp_f32_e32 v13, v12
	v_sub_f32_e32 v12, v88, v226
	v_sub_f32_e32 v2, v98, v226
	v_exp_f32_e32 v98, v11
	v_exp_f32_e32 v100, v12
	v_sub_f32_e32 v12, v104, v226
	v_sub_f32_e32 v84, v95, v226
	v_add_f32_e32 v95, 0, v4
	v_exp_f32_e32 v15, v12
	v_sub_f32_e32 v12, v89, v226
	v_add_f32_e32 v95, v5, v95
	v_sub_f32_e32 v10, v101, v226
	v_exp_f32_e32 v101, v12
	v_sub_f32_e32 v12, v105, v226
	v_add_f32_e32 v95, v6, v95
	v_exp_f32_e32 v17, v12
	v_sub_f32_e32 v12, v90, v226
	v_add_f32_e32 v95, v7, v95
	v_exp_f32_e32 v87, v12
	v_sub_f32_e32 v14, v91, v226
	v_add_f32_e32 v95, v98, v95
	v_exp_f32_e32 v88, v14
	v_sub_f32_e32 v16, v92, v226
	v_add_f32_e32 v95, v99, v95
	v_exp_f32_e32 v89, v16
	v_sub_f32_e32 v82, v93, v226
	v_add_f32_e32 v95, v100, v95
	v_exp_f32_e32 v90, v82
	v_sub_f32_e32 v83, v94, v226
	v_add_f32_e32 v95, v101, v95
	v_exp_f32_e32 v91, v83
	v_add_f32_e32 v95, v87, v95
	v_exp_f32_e32 v92, v84
	v_sub_f32_e32 v85, v96, v226
	v_add_f32_e32 v95, v88, v95
	v_exp_f32_e32 v93, v85
	v_sub_f32_e32 v86, v97, v226
	v_add_f32_e32 v95, v89, v95
	v_exp_f32_e32 v94, v86
	v_add_f32_e32 v95, v90, v95
	v_exp_f32_e32 v2, v2
	v_add_f32_e32 v95, v91, v95
	v_add_f32_e32 v95, v92, v95
	v_add_f32_e32 v95, v93, v95
	v_exp_f32_e32 v10, v10
	v_sub_f32_e32 v11, v102, v226
	v_add_f32_e32 v95, v94, v95
	v_exp_f32_e32 v11, v11
	v_add_f32_e32 v95, v2, v95
	v_add_f32_e32 v95, v8, v95
	v_add_f32_e32 v95, v9, v95
	v_sub_f32_e32 v12, v106, v226
	v_add_f32_e32 v95, v10, v95
	v_exp_f32_e32 v12, v12
	v_sub_f32_e32 v14, v107, v226
	v_add_f32_e32 v95, v11, v95
	v_exp_f32_e32 v14, v14
	v_sub_f32_e32 v16, v108, v226
	v_add_f32_e32 v95, v13, v95
	v_exp_f32_e32 v16, v16
	v_sub_f32_e32 v82, v109, v226
	v_add_f32_e32 v95, v15, v95
	v_exp_f32_e32 v82, v82
	v_sub_f32_e32 v83, v110, v226
	v_add_f32_e32 v95, v17, v95
	v_exp_f32_e32 v83, v83
	v_sub_f32_e32 v84, v111, v226
	v_add_f32_e32 v95, v12, v95
	v_exp_f32_e32 v84, v84
	v_sub_f32_e32 v85, v112, v226
	v_add_f32_e32 v95, v14, v95
	v_exp_f32_e32 v85, v85
	v_sub_f32_e32 v86, v113, v226
	v_add_f32_e32 v95, v16, v95
	v_exp_f32_e32 v86, v86
	v_add_f32_e32 v95, v82, v95
	v_add_f32_e32 v95, v83, v95
	v_add_f32_e32 v95, v84, v95
	v_add_f32_e32 v95, v85, v95
	v_add_f32_e32 v96, v86, v95
	v_exp_f32_e32 v95, v164
	v_mov_b32_e32 v97, v96
	s_nop 1
	v_permlane32_swap_b32_e32 v96, v97
	v_cmp_gt_f32_e32 vcc, 1.0, v95
	s_cbranch_vccz .LattB_960
	s_and_saveexec_b64 s[60:61], s[2:3]
	ds_write_b32 v206, v95 offset:128
	s_or_b64 exec, exec, s[60:61]
	s_waitcnt lgkmcnt(0)
	v_add_u32_e32 v164, s90, v162
	ds_read_b128 v[102:105], v164 offset:224
	ds_read_b128 v[106:109], v164 offset:192
	ds_read_b128 v[110:113], v164 offset:160
	ds_read_b128 v[228:231], v164 offset:128
	s_waitcnt lgkmcnt(0)
	v_pk_mul_f32 v[78:79], v[78:79], v[102:103]
	v_pk_mul_f32 v[74:75], v[74:75], v[106:107]
	v_pk_mul_f32 v[70:71], v[70:71], v[110:111]
	v_pk_mul_f32 v[80:81], v[80:81], v[104:105]
	v_pk_mul_f32 v[76:77], v[76:77], v[108:109]
	v_pk_mul_f32 v[72:73], v[72:73], v[112:113]
	v_pk_mul_f32 v[68:69], v[68:69], v[230:231]
	v_pk_mul_f32 v[66:67], v[66:67], v[228:229]
	v_pk_mul_f32 v[62:63], v[62:63], v[102:103]
	v_pk_mul_f32 v[58:59], v[58:59], v[106:107]
	v_pk_mul_f32 v[54:55], v[54:55], v[110:111]
	v_pk_mul_f32 v[64:65], v[64:65], v[104:105]
	v_pk_mul_f32 v[60:61], v[60:61], v[108:109]
	v_pk_mul_f32 v[56:57], v[56:57], v[112:113]
	v_pk_mul_f32 v[52:53], v[52:53], v[230:231]
	v_pk_mul_f32 v[50:51], v[50:51], v[228:229]
	v_pk_mul_f32 v[46:47], v[46:47], v[102:103]
	v_pk_mul_f32 v[42:43], v[42:43], v[106:107]
	v_pk_mul_f32 v[38:39], v[38:39], v[110:111]
	v_pk_mul_f32 v[48:49], v[48:49], v[104:105]
	v_pk_mul_f32 v[44:45], v[44:45], v[108:109]
	v_pk_mul_f32 v[40:41], v[40:41], v[112:113]
	v_pk_mul_f32 v[36:37], v[36:37], v[230:231]
	v_pk_mul_f32 v[34:35], v[34:35], v[228:229]
	v_pk_mul_f32 v[30:31], v[30:31], v[102:103]
	v_pk_mul_f32 v[26:27], v[26:27], v[106:107]
	v_pk_mul_f32 v[22:23], v[22:23], v[110:111]
	v_pk_mul_f32 v[32:33], v[32:33], v[104:105]
	v_pk_mul_f32 v[28:29], v[28:29], v[108:109]
	v_pk_mul_f32 v[24:25], v[24:25], v[112:113]
	v_pk_mul_f32 v[20:21], v[20:21], v[230:231]
	v_pk_mul_f32 v[18:19], v[18:19], v[228:229]

; template <int VB>
; __device__ __forceinline__ void pv_tile(f32x16* o, int vb0, bf16x8 pa0, bf16x8 pa1, bf16x8 pa2, bf16x8 pa3) {
;     ...
;     PV_D0(0); PV_D0(1); PV_D0(2); PV_D0(3);
; template <int VAR>
; __device__ __forceinline__ void attn_unit(const AUnit& u, LAS char* lds) {
;     ...
;     for (int j = 0; j < u.nt; j += 2) {
;         ASTEP(0, j);
;         if (j + 1 < u.nt) ASTEP(1, j + 1);
;     }
.Latt_h4sB_join:
	s_waitcnt lgkmcnt(0)
	s_barrier
	v_lshl_add_u64 v[172:173], v[172:173], 0, s[26:27]
	v_lshl_add_u64 v[174:175], v[174:175], 0, s[26:27]
	v_lshl_add_u64 v[176:177], v[176:177], 0, s[16:17]
	v_lshl_add_u64 v[178:179], v[178:179], 0, s[26:27]
	s_add_i32 s19, s19, 2
	s_cmp_ge_u32 s19, s57
	s_cbranch_scc0 .Latt_topB
	s_add_i32 s95, s19, -1
	s_cmp_le_i32 s95, s91
	s_cselect_b64 s[96:97], -1, 0
	s_and_b64 s[96:97], s[58:59], s[96:97]
	s_andn2_b64 vcc, exec, s[96:97]
	s_cbranch_vccnz .Latt_h5pB_skip
	ds_read_b64_tr_b16 v[82:83], v163 offset:0x4000
	ds_read_b64_tr_b16 v[84:85], v163 offset:0x4800
	ds_read_b64_tr_b16 v[92:93], v163 offset:0x5000
	ds_read_b64_tr_b16 v[94:95], v163 offset:0x5800
	ds_read_b64_tr_b16 v[96:97], v163 offset:0x6000
	ds_read_b64_tr_b16 v[98:99], v163 offset:0x6800
	ds_read_b64_tr_b16 v[100:101], v163 offset:0x7000
	ds_read_b64_tr_b16 v[102:103], v163 offset:0x7800
	s_waitcnt lgkmcnt(0)
	s_nop 0
	v_mfma_f32_32x32x16_bf16 v[66:81], v[4:7], v[82:85], v[66:81]
	ds_read_b64_tr_b16 v[82:83], v163 offset:0x4200
	ds_read_b64_tr_b16 v[84:85], v163 offset:0x4a00
	v_mfma_f32_32x32x16_bf16 v[66:81], v[88:91], v[92:95], v[66:81]
	ds_read_b64_tr_b16 v[92:93], v163 offset:0x5200
	ds_read_b64_tr_b16 v[94:95], v163 offset:0x5a00
	v_mfma_f32_32x32x16_bf16 v[66:81], v[8:11], v[96:99], v[66:81]
	ds_read_b64_tr_b16 v[96:97], v163 offset:0x6200
	ds_read_b64_tr_b16 v[98:99], v163 offset:0x6a00
	v_mfma_f32_32x32x16_bf16 v[66:81], v[12:15], v[100:103], v[66:81]
	ds_read_b64_tr_b16 v[100:101], v163 offset:0x7200
	ds_read_b64_tr_b16 v[102:103], v163 offset:0x7a00
	s_waitcnt lgkmcnt(0)
	v_mfma_f32_32x32x16_bf16 v[50:65], v[4:7], v[82:85], v[50:65]
	ds_read_b64_tr_b16 v[82:83], v163 offset:0x4400
	ds_read_b64_tr_b16 v[84:85], v163 offset:0x4c00
	v_mfma_f32_32x32x16_bf16 v[50:65], v[88:91], v[92:95], v[50:65]
	ds_read_b64_tr_b16 v[92:93], v163 offset:0x5400
	ds_read_b64_tr_b16 v[94:95], v163 offset:0x5c00
	v_mfma_f32_32x32x16_bf16 v[50:65], v[8:11], v[96:99], v[50:65]
	ds_read_b64_tr_b16 v[96:97], v163 offset:0x6400
	ds_read_b64_tr_b16 v[98:99], v163 offset:0x6c00
	v_mfma_f32_32x32x16_bf16 v[50:65], v[12:15], v[100:103], v[50:65]
	ds_read_b64_tr_b16 v[100:101], v163 offset:0x7400
	ds_read_b64_tr_b16 v[102:103], v163 offset:0x7c00
	s_waitcnt lgkmcnt(0)
	v_mfma_f32_32x32x16_bf16 v[34:49], v[4:7], v[82:85], v[34:49]
	ds_read_b64_tr_b16 v[82:83], v163 offset:0x4600
	ds_read_b64_tr_b16 v[84:85], v163 offset:0x4e00
	v_mfma_f32_32x32x16_bf16 v[34:49], v[88:91], v[92:95], v[34:49]
	ds_read_b64_tr_b16 v[92:93], v163 offset:0x5600
	ds_read_b64_tr_b16 v[94:95], v163 offset:0x5e00
	v_mfma_f32_32x32x16_bf16 v[34:49], v[8:11], v[96:99], v[34:49]
	ds_read_b64_tr_b16 v[96:97], v163 offset:0x6600
	ds_read_b64_tr_b16 v[98:99], v163 offset:0x6e00
	v_mfma_f32_32x32x16_bf16 v[34:49], v[12:15], v[100:103], v[34:49]
	ds_read_b64_tr_b16 v[100:101], v163 offset:0x7600
	ds_read_b64_tr_b16 v[102:103], v163 offset:0x7e00
	s_waitcnt lgkmcnt(0)
	v_mfma_f32_32x32x16_bf16 v[18:33], v[4:7], v[82:85], v[18:33]
	v_mfma_f32_32x32x16_bf16 v[18:33], v[88:91], v[92:95], v[18:33]
	v_mfma_f32_32x32x16_bf16 v[18:33], v[8:11], v[96:99], v[18:33]
	v_mfma_f32_32x32x16_bf16 v[18:33], v[12:15], v[100:103], v[18:33]
.Latt_h5pB_skip:
	s_waitcnt vmcnt(0)
	s_waitcnt lgkmcnt(0)
	s_barrier
	s_add_i32 s92, s19, 0
